# speedup vs baseline: 1.0360x; 1.0111x over previous
; DI int obid() { int b = blockIdx.x; asm volatile("" : "+s"(b)); return b; }
; DI f32x4 h4_to_f4(u32x2 t) { const h16x4 h = __builtin_bit_cast(h16x4, t); return (f32x4){(float)h[0], (float)h[1], (float)h[2], (float)h[3]}; }
; DI void phase_row(const Params& P, const void* xs, int sh, void* xd, int dh, int ln, int gl, int gidx, float wgt, int modl, int shidx, bool dry = false) {
;     ...
;     for (int row = obid() * 8 + w; row < T; row += gridDim.x * 8) {
;         const int b = row >= SEQ;
;         f32x4 v[4];
; #pragma unroll
;         for (int j = 0; j < 4; ++j) { const size_t e = (size_t)row * D + 4 * lane + 256 * j;
;             if (sh) v[j] = h4_to_f4(__builtin_nontemporal_load((const u32x2*)((const unsigned short*)xs + e))); else v[j] = __builtin_nontemporal_load((const f32x4*)((const float*)xs + e)); }
;         if (ln >= 0) {
;             u32x2 fv[4];
; #pragma unroll
;             for (int j = 0; j < 4; ++j) fv[j] = __builtin_nontemporal_load((const u32x2*)(U + (size_t)row * D + 4 * lane + 256 * j));
;             const float* gate = mod + (gl * 2 + b) * 9216 + gidx * 1024;
; #pragma unroll
;             for (int j = 0; j < 4; ++j) { const f32x4 g = (*(const f32x4*)(gate + 4 * lane + 256 * j) + 1.f) * wgt;
;     ...
;             const float* shp = mod + (modl * 2 + b) * 9216 + shidx * 1024; const float* sc = shp + 1024;
; #pragma unroll
;             for (int j = 0; j < 4; ++j) { const f32x4 s4 = *(const f32x4*)(shp + 4 * lane + 256 * j), c4 = *(const f32x4*)(sc + 4 * lane + 256 * j);
.LBB0_19:
	s_cbranch_execz .LBB0_25
	v_readlane_b32 s2, v245, 33
	s_cmp_eq_u32 s2, 25
	s_mov_b64 s[48:49], -1
	s_cbranch_scc0 .LBB0_25
	s_load_dwordx8 s[60:67], s[84:85], 0xc8
	s_waitcnt vmcnt(0)
	v_mov_b32_e32 v0, v195
	s_mov_b32 s2, s28
	s_waitcnt lgkmcnt(0)
	s_mov_b64 s[30:31], s[66:67]
	s_mov_b64 s[26:27], s[66:67]
	v_ashrrev_i32_e32 v1, 6, v0
	s_mov_b64 s[40:41], s[66:67]
	s_nop 0
	v_lshl_add_u32 v48, s2, 3, v1
	v_cmp_gt_i32_e32 vcc, s75, v48
	s_and_saveexec_b64 s[2:3], vcc
	s_mov_b32 s42, 0x3fb504f3
	s_mov_b64 s[46:47], 0x1000
	s_cbranch_execz .LBB0_24
	v_lshlrev_b32_e32 v0, 2, v0
	s_load_dwordx16 s[48:63], s[84:85], 0x0
	v_and_b32_e32 v50, 0xfc, v0
	s_add_u32 s30, s30, 0x16008000
	v_lshlrev_b32_e32 v184, 1, v50
	s_addc_u32 s31, s31, 0
	v_lshl_add_u64 v[0:1], s[40:41], 0, v[184:185]
	s_mov_b64 s[36:37], 0x5808000
	v_lshlrev_b32_e32 v184, 2, v50
	v_lshl_add_u64 v[52:53], v[0:1], 0, s[36:37]
	v_lshl_add_u64 v[0:1], s[26:27], 0, v[184:185]
	s_mov_b64 s[36:37], 0x5585000
	s_add_u32 s40, s26, 0x5586000
	v_lshl_add_u64 v[54:55], v[0:1], 0, s[36:37]
	s_addc_u32 s41, s27, 0
	s_waitcnt lgkmcnt(0)
	v_lshl_add_u64 v[0:1], s[62:63], 0, v[184:185]
	s_mov_b64 s[26:27], 0x4000
	v_lshl_add_u64 v[56:57], v[0:1], 0, s[26:27]
	v_lshl_add_u64 v[0:1], s[4:5], 0, v[184:185]
	v_lshl_add_u64 v[58:59], v[0:1], 0, s[26:27]
	s_mov_b64 s[44:45], 0
	global_load_dwordx4 v[116:119], v[56:57], off
	global_load_dwordx4 v[108:111], v[56:57], off offset:1024
	global_load_dwordx4 v[132:135], v[58:59], off
	global_load_dwordx4 v[124:127], v[58:59], off offset:1024
	global_load_dwordx4 v[120:123], v[56:57], off offset:2048
	global_load_dwordx4 v[112:115], v[56:57], off offset:3072
	global_load_dwordx4 v[136:139], v[58:59], off offset:2048
	global_load_dwordx4 v[128:131], v[58:59], off offset:3072
	v_mov_b32_e32 v184, v196
	v_lshl_add_u64 v[106:107], v[54:55], 0, v[184:185]
	flat_load_dwordx4 v[140:143], v[106:107]
	flat_load_dwordx4 v[144:147], v[106:107] offset:1024
	flat_load_dwordx4 v[148:151], v[106:107] offset:2048
	flat_load_dwordx4 v[152:155], v[106:107] offset:3072
	v_mov_b32_e32 v184, v197
	v_lshl_add_u64 v[106:107], v[54:55], 0, v[184:185]
	flat_load_dwordx4 v[156:159], v[106:107]
	flat_load_dwordx4 v[160:163], v[106:107] offset:1024
	flat_load_dwordx4 v[164:167], v[106:107] offset:2048
	flat_load_dwordx4 v[168:171], v[106:107] offset:3072
	s_waitcnt vmcnt(0) lgkmcnt(0)
	s_mov_b64 s[100:101], 1
.LBB0_23:
	v_ashrrev_i32_e32 v49, 31, v48
	v_cmp_lt_i32_e32 vcc, s23, v48
	v_lshlrev_b64 v[72:73], 11, v[48:49]
	v_lshl_or_b32 v88, v50, 1, v72
	v_cndmask_b32_e32 v184, v196, v197, vcc
	v_mov_b32_e32 v89, v73
	v_lshl_add_u64 v[32:33], v[54:55], 0, v[184:185]
	v_lshl_add_u64 v[60:61], v[52:53], 0, v[72:73]
	v_lshl_add_u64 v[68:69], s[64:65], 0, v[88:89]
	v_cndmask_b32_e32 v44, v140, v156, vcc
	v_cndmask_b32_e32 v45, v141, v157, vcc
	v_cndmask_b32_e32 v46, v142, v158, vcc
	v_cndmask_b32_e32 v47, v143, v159, vcc
	v_cndmask_b32_e32 v40, v144, v160, vcc
	v_cndmask_b32_e32 v41, v145, v161, vcc
	v_cndmask_b32_e32 v42, v146, v162, vcc
	v_cndmask_b32_e32 v43, v147, v163, vcc
	v_cndmask_b32_e32 v36, v148, v164, vcc
	v_cndmask_b32_e32 v37, v149, v165, vcc
	v_cndmask_b32_e32 v38, v150, v166, vcc
	v_cndmask_b32_e32 v39, v151, v167, vcc
	v_cndmask_b32_e32 v32, v152, v168, vcc
	v_cndmask_b32_e32 v33, v153, v169, vcc
	v_cndmask_b32_e32 v34, v154, v170, vcc
	v_cndmask_b32_e32 v35, v155, v171, vcc
	s_nop 0
	s_nop 0
	flat_load_dwordx2 v[84:85], v[60:61] nt
	flat_load_dwordx2 v[80:81], v[60:61] offset:512 nt
	flat_load_dwordx2 v[76:77], v[60:61] offset:1024 nt
	flat_load_dwordx2 v[70:71], v[60:61] offset:1536 nt
	global_load_dwordx2 v[86:87], v[68:69], off nt
	global_load_dwordx2 v[82:83], v[68:69], off offset:512 nt
	global_load_dwordx2 v[78:79], v[68:69], off offset:1024 nt
	global_load_dwordx2 v[74:75], v[68:69], off offset:1536 nt
	v_or_b32_e32 v72, 0x200, v88
	v_lshl_add_u64 v[68:69], s[30:31], 0, v[72:73]
	v_or_b32_e32 v72, 0x400, v88
	v_lshl_add_u64 v[66:67], s[30:31], 0, v[88:89]
	v_lshl_add_u64 v[90:91], s[30:31], 0, v[72:73]
	v_or_b32_e32 v72, 0x600, v88
	v_lshl_add_u64 v[62:63], s[40:41], 0, v[184:185]
	v_lshlrev_b32_e32 v184, 2, v50
	v_lshl_add_u64 v[62:63], v[62:63], 0, v[184:185]
	s_cmp_eq_u64 vcc, s[100:101]
	s_cbranch_scc1 .Lrow_keep_0
	s_mov_b64 s[100:101], vcc
	v_lshl_add_u64 v[106:107], v[62:63], 0, s[46:47]
	flat_load_dwordx4 v[208:211], v[106:107]
	flat_load_dwordx4 v[212:215], v[62:63]
	flat_load_dwordx4 v[216:219], v[106:107] offset:1024
	flat_load_dwordx4 v[220:223], v[62:63] offset:1024
	flat_load_dwordx4 v[224:227], v[106:107] offset:2048
	flat_load_dwordx4 v[228:231], v[62:63] offset:2048
	flat_load_dwordx4 v[232:235], v[106:107] offset:3072
	flat_load_dwordx4 v[236:239], v[62:63] offset:3072
; DI float bf_lo(unsigned u) { return __uint_as_float(u << 16); }
; DI float bf_hi(unsigned u) { return __uint_as_float(u & 0xffff0000u); }
; DI f32x4 h4_to_f4(u32x2 t) { const h16x4 h = __builtin_bit_cast(h16x4, t); return (f32x4){(float)h[0], (float)h[1], (float)h[2], (float)h[3]}; }
; DI void phase_row(const Params& P, const void* xs, int sh, void* xd, int dh, int ln, int gl, int gidx, float wgt, int modl, int shidx, bool dry = false) {
;     ...
;         for (int j = 0; j < 4; ++j) { const size_t e = (size_t)row * D + 4 * lane + 256 * j;
;             if (sh) v[j] = h4_to_f4(__builtin_nontemporal_load((const u32x2*)((const unsigned short*)xs + e))); else v[j] = __builtin_nontemporal_load((const f32x4*)((const float*)xs + e)); }
;         if (ln >= 0) {
;             u32x2 fv[4];
; #pragma unroll
;             for (int j = 0; j < 4; ++j) fv[j] = __builtin_nontemporal_load((const u32x2*)(U + (size_t)row * D + 4 * lane + 256 * j));
;             const float* gate = mod + (gl * 2 + b) * 9216 + gidx * 1024;
; #pragma unroll
;             for (int j = 0; j < 4; ++j) { const f32x4 g = (*(const f32x4*)(gate + 4 * lane + 256 * j) + 1.f) * wgt;
;                 const f32x4 f = {bf_lo(fv[j].x), bf_hi(fv[j].x), bf_lo(fv[j].y), bf_hi(fv[j].y)};
;                 v[j] = v[j] * DN_ALPHA + g * f; }
;             float s = 0.f;
; #pragma unroll
;             for (int j = 0; j < 4; ++j) s += (v[j][0] + v[j][1]) + (v[j][2] + v[j][3]);
;             const float mean = wave_sum(s, lane) * (1.f / 1024.f);
;             float q = 0.f;
; #pragma unroll
;             for (int j = 0; j < 4; ++j) { v[j] = v[j] - mean; q += (v[j][0] * v[j][0] + v[j][1] * v[j][1]) + (v[j][2] * v[j][2] + v[j][3] * v[j][3]); }
.Lrow_keep_0:
	v_add_co_u32_e32 v64, vcc, s1, v62
	v_lshl_add_u64 v[72:73], s[30:31], 0, v[72:73]
	s_nop 0
	v_addc_co_u32_e32 v65, vcc, 0, v63, vcc
	v_add_u32_e32 v48, s70, v48
	s_waitcnt vmcnt(0) lgkmcnt(0)
	v_pk_add_f32 v[46:47], v[46:47], 1.0 op_sel_hi:[1,0]
	v_pk_add_f32 v[44:45], v[44:45], 1.0 op_sel_hi:[1,0]
	v_cvt_f32_f16_e32 v98, v86
	v_cvt_f32_f16_sdwa v99, v86 dst_sel:DWORD dst_unused:UNUSED_PAD src0_sel:WORD_1
	v_cvt_f32_f16_e32 v86, v87
	v_cvt_f32_f16_sdwa v87, v87 dst_sel:DWORD dst_unused:UNUSED_PAD src0_sel:WORD_1
	v_cvt_f32_f16_e32 v100, v82
	v_cvt_f32_f16_sdwa v101, v82 dst_sel:DWORD dst_unused:UNUSED_PAD src0_sel:WORD_1
	v_cvt_f32_f16_e32 v82, v83
	v_cvt_f32_f16_sdwa v83, v83 dst_sel:DWORD dst_unused:UNUSED_PAD src0_sel:WORD_1
	v_lshlrev_b32_e32 v88, 16, v84
	v_and_b32_e32 v89, 0xffff0000, v84
	v_lshlrev_b32_e32 v84, 16, v85
	v_and_b32_e32 v85, 0xffff0000, v85
	v_cvt_f32_f16_e32 v102, v78
	v_cvt_f32_f16_sdwa v103, v78 dst_sel:DWORD dst_unused:UNUSED_PAD src0_sel:WORD_1
	v_cvt_f32_f16_e32 v78, v79
	v_cvt_f32_f16_sdwa v79, v79 dst_sel:DWORD dst_unused:UNUSED_PAD src0_sel:WORD_1
	v_pk_add_f32 v[42:43], v[42:43], 1.0 op_sel_hi:[1,0]
	v_pk_add_f32 v[40:41], v[40:41], 1.0 op_sel_hi:[1,0]
	v_lshlrev_b32_e32 v92, 16, v80
	v_and_b32_e32 v93, 0xffff0000, v80
	v_lshlrev_b32_e32 v80, 16, v81
	v_and_b32_e32 v81, 0xffff0000, v81
	v_cvt_f32_f16_e32 v104, v74
	v_cvt_f32_f16_sdwa v105, v74 dst_sel:DWORD dst_unused:UNUSED_PAD src0_sel:WORD_1
	v_cvt_f32_f16_e32 v74, v75
	v_cvt_f32_f16_sdwa v75, v75 dst_sel:DWORD dst_unused:UNUSED_PAD src0_sel:WORD_1
	v_pk_mul_f32 v[46:47], v[46:47], v[84:85]
	v_pk_mul_f32 v[44:45], v[44:45], v[88:89]
	v_pk_add_f32 v[38:39], v[38:39], 1.0 op_sel_hi:[1,0]
	v_pk_add_f32 v[36:37], v[36:37], 1.0 op_sel_hi:[1,0]
	v_lshlrev_b32_e32 v94, 16, v76
	v_and_b32_e32 v95, 0xffff0000, v76
	v_lshlrev_b32_e32 v76, 16, v77
	v_and_b32_e32 v77, 0xffff0000, v77
	v_pk_mul_f32 v[42:43], v[42:43], v[80:81]
	v_pk_mul_f32 v[40:41], v[40:41], v[92:93]
	v_pk_fma_f32 v[46:47], v[86:87], s[42:43], v[46:47] op_sel_hi:[1,0,1]
	v_pk_fma_f32 v[44:45], v[98:99], s[42:43], v[44:45] op_sel_hi:[1,0,1]
	v_pk_add_f32 v[34:35], v[34:35], 1.0 op_sel_hi:[1,0]
	v_pk_add_f32 v[32:33], v[32:33], 1.0 op_sel_hi:[1,0]
	v_lshlrev_b32_e32 v96, 16, v70
	v_and_b32_e32 v97, 0xffff0000, v70
	v_lshlrev_b32_e32 v70, 16, v71
	v_and_b32_e32 v71, 0xffff0000, v71
	v_pk_mul_f32 v[38:39], v[38:39], v[76:77]
	v_pk_mul_f32 v[36:37], v[36:37], v[94:95]
	v_pk_fma_f32 v[42:43], v[82:83], s[42:43], v[42:43] op_sel_hi:[1,0,1]
	v_pk_fma_f32 v[40:41], v[100:101], s[42:43], v[40:41] op_sel_hi:[1,0,1]
	v_add_f32_e32 v49, v44, v45
	v_add_f32_e32 v51, v46, v47
	v_pk_mul_f32 v[34:35], v[34:35], v[70:71]
	v_pk_mul_f32 v[32:33], v[32:33], v[96:97]
	v_pk_fma_f32 v[38:39], v[78:79], s[42:43], v[38:39] op_sel_hi:[1,0,1]
	v_pk_fma_f32 v[36:37], v[102:103], s[42:43], v[36:37] op_sel_hi:[1,0,1]
	v_add_f32_e32 v70, v40, v41
	v_add_f32_e32 v71, v42, v43
	v_add_f32_e32 v49, v49, v51
	v_pk_fma_f32 v[34:35], v[74:75], s[42:43], v[34:35] op_sel_hi:[1,0,1]
	v_pk_fma_f32 v[32:33], v[104:105], s[42:43], v[32:33] op_sel_hi:[1,0,1]
	v_add_f32_e32 v74, v36, v37
	v_add_f32_e32 v75, v38, v39
	v_add_f32_e32 v51, v70, v71
	v_add_f32_e32 v49, 0, v49
	v_add_f32_e32 v76, v32, v33
	v_add_f32_e32 v77, v34, v35
	v_add_f32_e32 v70, v74, v75
	v_add_f32_e32 v49, v49, v51
	v_add_f32_e32 v71, v76, v77
	v_add_f32_e32 v49, v49, v70
	v_add_f32_e32 v49, v49, v71
	s_nop 1
	v_add_f32_dpp v49, v49, v49 quad_perm:[1,0,3,2] row_mask:0xf bank_mask:0xf bound_ctrl:1
	s_nop 1
	v_add_f32_dpp v49, v49, v49 quad_perm:[2,3,0,1] row_mask:0xf bank_mask:0xf bound_ctrl:1
	s_nop 1
	v_add_f32_dpp v49, v49, v49 row_half_mirror row_mask:0xf bank_mask:0xf bound_ctrl:1
	s_nop 1
	v_add_f32_dpp v49, v49, v49 row_mirror row_mask:0xf bank_mask:0xf bound_ctrl:1
	v_mov_b32_e32 v51, v49
	s_nop 1
	v_permlane16_swap_b32_e32 v49, v51
	v_add_f32_e32 v49, v49, v51
	v_mov_b32_e32 v51, v49
	s_nop 1
	v_permlane32_swap_b32_e32 v49, v51
	v_add_f32_e32 v49, v49, v51
	v_fmac_f32_e32 v47, 0xba800000, v49
	v_fmac_f32_e32 v45, 0xba800000, v49
	v_fmac_f32_e32 v43, 0xba800000, v49
	v_fmac_f32_e32 v41, 0xba800000, v49
	v_fmamk_f32 v46, v49, 0xba800000, v46
	v_fmamk_f32 v44, v49, 0xba800000, v44
	v_fmamk_f32 v42, v49, 0xba800000, v42
	v_fmamk_f32 v40, v49, 0xba800000, v40
	v_fmamk_f32 v38, v49, 0xba800000, v38
	v_fmac_f32_e32 v39, 0xba800000, v49
	v_fmamk_f32 v36, v49, 0xba800000, v36
	v_fmac_f32_e32 v37, 0xba800000, v49
; DI unsigned pk_bf16(float lo, float hi) { unsigned r; asm("v_cvt_pk_bf16_f32 %0, %1, %2" : "=v"(r) : "v"(lo), "v"(hi)); return r; }
; DI void phase_row(const Params& P, const void* xs, int sh, void* xd, int dh, int ln, int gl, int gidx, float wgt, int modl, int shidx, bool dry = false) {
;     ...
;             for (int j = 0; j < 4; ++j) { v[j] = v[j] - mean; q += (v[j][0] * v[j][0] + v[j][1] * v[j][1]) + (v[j][2] * v[j][2] + v[j][3] * v[j][3]); }
;             const float rstd = rsqrtf(wave_sum(q, lane) * (1.f / 1024.f) + LN_EPS);
; #pragma unroll
;             for (int j = 0; j < 4; ++j) { const f32x4 g = *(const f32x4*)(P.ln_g + ln * D + 4 * lane + 256 * j), bb = *(const f32x4*)(P.ln_b + ln * D + 4 * lane + 256 * j); v[j] = v[j] * rstd * g + bb; }
;             if (dry) { if (v[0][0] + v[1][1] + v[2][2] + v[3][3] == 12345.678f) P.xbuf[row] = 0.f; continue; }
; #pragma unroll
;             for (int j = 0; j < 4; ++j) { const size_t e = (size_t)row * D + 4 * lane + 256 * j;
;                 if (dh) __builtin_nontemporal_store(f4_to_h4(v[j]), (u32x2*)((unsigned short*)xd + e)); else __builtin_nontemporal_store(v[j], (f32x4*)((float*)xd + e)); }
;         }
;         if (modl >= 0) {
;             const float* shp = mod + (modl * 2 + b) * 9216 + shidx * 1024; const float* sc = shp + 1024;
; #pragma unroll
;             for (int j = 0; j < 4; ++j) { const f32x4 s4 = *(const f32x4*)(shp + 4 * lane + 256 * j), c4 = *(const f32x4*)(sc + 4 * lane + 256 * j);
;                 const f32x4 u = v[j] * (c4 + 1.f) + s4; u32x2 o; o.x = pk_bf16(u[0], u[1]); o.y = pk_bf16(u[2], u[3]);
;                 *(u32x2*)(U + (size_t)row * D + 4 * lane + 256 * j) = o; }
	v_fmamk_f32 v34, v49, 0xba800000, v34
	v_fmac_f32_e32 v35, 0xba800000, v49
	v_fmamk_f32 v32, v49, 0xba800000, v32
	v_fmac_f32_e32 v33, 0xba800000, v49
	v_mul_f32_e32 v49, v45, v45
	v_mul_f32_e32 v51, v47, v47
	v_mul_f32_e32 v70, v41, v41
	v_mul_f32_e32 v71, v43, v43
	v_mul_f32_e32 v74, v37, v37
	v_mul_f32_e32 v75, v39, v39
	v_fmac_f32_e32 v49, v44, v44
	v_fmac_f32_e32 v51, v46, v46
	v_fmac_f32_e32 v70, v40, v40
	v_fmac_f32_e32 v71, v42, v42
	v_mul_f32_e32 v76, v33, v33
	v_mul_f32_e32 v77, v35, v35
	v_fmac_f32_e32 v74, v36, v36
	v_fmac_f32_e32 v75, v38, v38
	v_add_f32_e32 v49, v49, v51
	v_add_f32_e32 v51, v70, v71
	v_fmac_f32_e32 v76, v32, v32
	v_fmac_f32_e32 v77, v34, v34
	v_add_f32_e32 v70, v74, v75
	v_add_f32_e32 v49, v49, v51
	v_add_f32_e32 v71, v76, v77
	v_add_f32_e32 v49, v70, v49
	v_add_f32_e32 v49, v71, v49
	s_nop 1
	v_add_f32_dpp v49, v49, v49 quad_perm:[1,0,3,2] row_mask:0xf bank_mask:0xf bound_ctrl:1
	s_nop 1
	v_add_f32_dpp v49, v49, v49 quad_perm:[2,3,0,1] row_mask:0xf bank_mask:0xf bound_ctrl:1
	s_nop 1
	v_add_f32_dpp v49, v49, v49 row_half_mirror row_mask:0xf bank_mask:0xf bound_ctrl:1
	s_nop 1
	v_add_f32_dpp v49, v49, v49 row_mirror row_mask:0xf bank_mask:0xf bound_ctrl:1
	v_mov_b32_e32 v51, v49
	s_nop 1
	v_permlane16_swap_b32_e32 v49, v51
	v_add_f32_e32 v49, v49, v51
	v_mov_b32_e32 v51, v49
	s_nop 1
	v_permlane32_swap_b32_e32 v49, v51
	v_add_f32_e32 v49, v49, v51
	v_fmamk_f32 v49, v49, 0x3a800000, v198
	v_mul_f32_e32 v51, 0x4b800000, v49
	v_cmp_gt_f32_e32 vcc, s25, v49
	s_nop 1
	v_cndmask_b32_e32 v49, v49, v51, vcc
	v_rsq_f32_e32 v49, v49
	s_nop 0
	v_mul_f32_e32 v51, 0x45800000, v49
	v_cndmask_b32_e32 v70, v49, v51, vcc
	v_pk_mul_f32 v[46:47], v[46:47], v[70:71] op_sel_hi:[1,0]
	v_pk_mul_f32 v[44:45], v[44:45], v[70:71] op_sel_hi:[1,0]
	v_pk_mul_f32 v[40:41], v[40:41], v[70:71] op_sel_hi:[1,0]
	v_pk_mul_f32 v[42:43], v[42:43], v[70:71] op_sel_hi:[1,0]
	v_pk_mul_f32 v[36:37], v[36:37], v[70:71] op_sel_hi:[1,0]
	v_pk_mul_f32 v[38:39], v[38:39], v[70:71] op_sel_hi:[1,0]
	v_pk_mul_f32 v[32:33], v[32:33], v[70:71] op_sel_hi:[1,0]
	v_pk_mul_f32 v[34:35], v[34:35], v[70:71] op_sel_hi:[1,0]
	v_pk_fma_f32 v[8:9], v[116:117], v[44:45], v[132:133]
	v_pk_fma_f32 v[10:11], v[118:119], v[46:47], v[134:135]
	v_pk_fma_f32 v[18:19], v[110:111], v[42:43], v[126:127]
	v_pk_fma_f32 v[16:17], v[108:109], v[40:41], v[124:125]
	v_pk_fma_f32 v[14:15], v[122:123], v[38:39], v[138:139]
	v_pk_fma_f32 v[12:13], v[120:121], v[36:37], v[136:137]
	v_pk_fma_f32 v[22:23], v[114:115], v[34:35], v[130:131]
	v_pk_fma_f32 v[20:21], v[112:113], v[32:33], v[128:129]
	v_cvt_pk_f16_f32 v1, v10, v11
	v_cvt_pk_f16_f32 v0, v8, v9
	v_cvt_pk_f16_f32 v3, v18, v19
	v_cvt_pk_f16_f32 v2, v16, v17
	v_cvt_pk_f16_f32 v5, v14, v15
	v_cvt_pk_f16_f32 v4, v12, v13
	v_cvt_pk_f16_f32 v7, v22, v23
	v_cvt_pk_f16_f32 v6, v20, v21
	flat_store_dwordx2 v[66:67], v[0:1] nt
	flat_store_dwordx2 v[68:69], v[2:3] nt
	flat_store_dwordx2 v[90:91], v[4:5] nt
	flat_store_dwordx2 v[72:73], v[6:7] nt
	v_lshl_add_u64 v[24:25], v[62:63], 0, s[46:47]
	v_cmp_lt_i32_e32 vcc, s20, v48
	s_or_b64 s[44:45], vcc, s[44:45]
	v_pk_add_f32 v[0:1], v[208:209], 1.0 op_sel_hi:[1,0]
	v_pk_add_f32 v[2:3], v[210:211], 1.0 op_sel_hi:[1,0]
	v_pk_fma_f32 v[0:1], v[8:9], v[0:1], v[212:213]
	v_pk_fma_f32 v[2:3], v[10:11], v[2:3], v[214:215]
	v_cvt_pk_bf16_f32 v0, v0, v1
	s_nop 0
	v_cvt_pk_bf16_f32 v1, v2, v3
	flat_store_dwordx2 v[60:61], v[0:1]
	v_pk_add_f32 v[0:1], v[216:217], 1.0 op_sel_hi:[1,0]
	v_pk_add_f32 v[2:3], v[218:219], 1.0 op_sel_hi:[1,0]
	v_pk_fma_f32 v[0:1], v[16:17], v[0:1], v[220:221]
	v_pk_fma_f32 v[2:3], v[18:19], v[2:3], v[222:223]
	v_cvt_pk_bf16_f32 v0, v0, v1
	s_nop 0
	v_cvt_pk_bf16_f32 v1, v2, v3
	flat_store_dwordx2 v[60:61], v[0:1] offset:512
	v_pk_add_f32 v[0:1], v[224:225], 1.0 op_sel_hi:[1,0]
	v_pk_add_f32 v[2:3], v[226:227], 1.0 op_sel_hi:[1,0]
	v_pk_fma_f32 v[0:1], v[12:13], v[0:1], v[228:229]
	v_pk_fma_f32 v[2:3], v[14:15], v[2:3], v[230:231]
	v_cvt_pk_bf16_f32 v0, v0, v1
	s_nop 0
	v_cvt_pk_bf16_f32 v1, v2, v3
	flat_store_dwordx2 v[60:61], v[0:1] offset:1024
	v_pk_add_f32 v[0:1], v[232:233], 1.0 op_sel_hi:[1,0]
	v_pk_add_f32 v[2:3], v[234:235], 1.0 op_sel_hi:[1,0]
	v_pk_fma_f32 v[0:1], v[20:21], v[0:1], v[236:237]
	v_pk_fma_f32 v[2:3], v[22:23], v[2:3], v[238:239]
	v_cvt_pk_bf16_f32 v0, v0, v1
	s_nop 0
	v_cvt_pk_bf16_f32 v1, v2, v3
	flat_store_dwordx2 v[60:61], v[0:1] offset:1536
	s_andn2_b64 exec, exec, s[44:45]
	s_cbranch_execnz .LBB0_23

; DI int obid() { int b = blockIdx.x; asm volatile("" : "+s"(b)); return b; }
; DI f32x4 h4_to_f4(u32x2 t) { const h16x4 h = __builtin_bit_cast(h16x4, t); return (f32x4){(float)h[0], (float)h[1], (float)h[2], (float)h[3]}; }
; DI void phase_row(const Params& P, const void* xs, int sh, void* xd, int dh, int ln, int gl, int gidx, float wgt, int modl, int shidx, bool dry = false) {
;     ...
;     for (int row = obid() * 8 + w; row < T; row += gridDim.x * 8) {
;         const int b = row >= SEQ;
;         f32x4 v[4];
; #pragma unroll
;         for (int j = 0; j < 4; ++j) { const size_t e = (size_t)row * D + 4 * lane + 256 * j;
;             if (sh) v[j] = h4_to_f4(__builtin_nontemporal_load((const u32x2*)((const unsigned short*)xs + e))); else v[j] = __builtin_nontemporal_load((const f32x4*)((const float*)xs + e)); }
;         if (ln >= 0) {
;             u32x2 fv[4];
; #pragma unroll
;             for (int j = 0; j < 4; ++j) fv[j] = __builtin_nontemporal_load((const u32x2*)(U + (size_t)row * D + 4 * lane + 256 * j));
;             const float* gate = mod + (gl * 2 + b) * 9216 + gidx * 1024;
; #pragma unroll
;             for (int j = 0; j < 4; ++j) { const f32x4 g = (*(const f32x4*)(gate + 4 * lane + 256 * j) + 1.f) * wgt;
;     ...
;             const float* shp = mod + (modl * 2 + b) * 9216 + shidx * 1024; const float* sc = shp + 1024;
; #pragma unroll
;             for (int j = 0; j < 4; ++j) { const f32x4 s4 = *(const f32x4*)(shp + 4 * lane + 256 * j), c4 = *(const f32x4*)(sc + 4 * lane + 256 * j);
.LBB0_95:
	s_and_b64 vcc, exec, s[2:3]
	s_cbranch_vccz .LBB0_101
	v_readlane_b32 s2, v245, 33
	s_cmp_eq_u32 s2, 17
	s_mov_b64 s[48:49], -1
	s_cbranch_scc0 .LBB0_101
	s_waitcnt vmcnt(0)
	v_mov_b32_e32 v0, v195
	s_load_dwordx8 s[40:47], s[84:85], 0xc8
	v_ashrrev_i32_e32 v1, 6, v0
	s_mov_b32 s2, s28
	s_waitcnt lgkmcnt(0)
	s_mov_b64 s[26:27], s[46:47]
	s_mov_b64 s[30:31], s[46:47]
	s_nop 0
	v_lshl_add_u32 v32, s2, 3, v1
	v_cmp_gt_i32_e32 vcc, s75, v32
	s_and_saveexec_b64 s[2:3], vcc
	s_mov_b32 s42, 0x3fb504f3
	s_mov_b64 s[44:45], 0x1000
	s_cbranch_execz .LBB0_100
	v_lshlrev_b32_e32 v0, 2, v0
	v_and_b32_e32 v0, 0xfc, v0
	v_lshlrev_b32_e32 v184, 1, v0
	s_load_dwordx16 s[48:63], s[84:85], 0x0
	v_lshl_add_u64 v[2:3], s[30:31], 0, v[184:185]
	s_mov_b64 s[30:31], 0x5808000
	s_waitcnt lgkmcnt(0)
	s_load_dwordx8 s[48:55], s[84:85], 0xc8
	v_lshl_add_u64 v[34:35], v[2:3], 0, s[30:31]
	v_lshlrev_b32_e32 v2, 2, v0
	v_mov_b32_e32 v3, v185
	v_lshl_add_u64 v[4:5], s[26:27], 0, v[2:3]
	s_mov_b64 s[30:31], 0x5582000
	v_lshl_add_u64 v[36:37], v[4:5], 0, s[30:31]
	s_add_u32 s30, s26, 0x5583000
	s_addc_u32 s31, s27, 0
	v_lshl_add_u64 v[4:5], s[62:63], 0, v[2:3]
	s_mov_b64 s[26:27], 0x3000
	v_lshl_add_u64 v[2:3], s[4:5], 0, v[2:3]
	s_mov_b64 s[60:61], 0
	v_lshl_add_u64 v[38:39], v[4:5], 0, s[26:27]
	v_lshl_add_u64 v[40:41], v[2:3], 0, s[26:27]
	s_waitcnt lgkmcnt(0)
	v_lshl_add_u64 v[42:43], s[52:53], 0, v[184:185]
	s_mov_b64 s[40:41], 0
	v_lshlrev_b32_e32 v44, 2, v0
	global_load_dwordx4 v[112:115], v[38:39], off
	global_load_dwordx4 v[104:107], v[38:39], off offset:1024
	global_load_dwordx4 v[128:131], v[40:41], off
	global_load_dwordx4 v[120:123], v[40:41], off offset:1024
	global_load_dwordx4 v[116:119], v[38:39], off offset:2048
	global_load_dwordx4 v[108:111], v[38:39], off offset:3072
	global_load_dwordx4 v[132:135], v[40:41], off offset:2048
	global_load_dwordx4 v[124:127], v[40:41], off offset:3072
	v_mov_b32_e32 v184, v196
	v_lshl_add_u64 v[102:103], v[36:37], 0, v[184:185]
	flat_load_dwordx4 v[136:139], v[102:103]
	flat_load_dwordx4 v[140:143], v[102:103] offset:1024
	flat_load_dwordx4 v[144:147], v[102:103] offset:2048
	flat_load_dwordx4 v[148:151], v[102:103] offset:3072
	v_mov_b32_e32 v184, v197
	v_lshl_add_u64 v[102:103], v[36:37], 0, v[184:185]
	flat_load_dwordx4 v[152:155], v[102:103]
	flat_load_dwordx4 v[156:159], v[102:103] offset:1024
	flat_load_dwordx4 v[160:163], v[102:103] offset:2048
	flat_load_dwordx4 v[164:167], v[102:103] offset:3072
	s_waitcnt vmcnt(0) lgkmcnt(0)
	s_mov_b64 s[100:101], 1
.LBB0_99:
	v_cmp_lt_i32_e32 vcc, s23, v32
	v_ashrrev_i32_e32 v33, 31, v32
	v_lshlrev_b64 v[48:49], 11, v[32:33]
	v_cndmask_b32_e32 v184, v196, v197, vcc
	v_lshl_add_u64 v[46:47], v[36:37], 0, v[184:185]
	v_mov_b32_e32 v45, v185
	v_lshl_add_u64 v[68:69], s[30:31], 0, v[184:185]
	v_cndmask_b32_e32 v52, v136, v152, vcc
	v_cndmask_b32_e32 v53, v137, v153, vcc
	v_cndmask_b32_e32 v54, v138, v154, vcc
	v_cndmask_b32_e32 v55, v139, v155, vcc
	v_cndmask_b32_e32 v56, v140, v156, vcc
	v_cndmask_b32_e32 v57, v141, v157, vcc
	v_cndmask_b32_e32 v58, v142, v158, vcc
	v_cndmask_b32_e32 v59, v143, v159, vcc
	v_cndmask_b32_e32 v60, v144, v160, vcc
	v_cndmask_b32_e32 v61, v145, v161, vcc
	v_cndmask_b32_e32 v62, v146, v162, vcc
	v_cndmask_b32_e32 v63, v147, v163, vcc
	v_cndmask_b32_e32 v64, v148, v164, vcc
	v_cndmask_b32_e32 v65, v149, v165, vcc
	v_cndmask_b32_e32 v66, v150, v166, vcc
	v_cndmask_b32_e32 v67, v151, v167, vcc
	v_lshl_add_u64 v[50:51], v[42:43], 0, v[48:49]
	v_lshl_add_u64 v[46:47], v[34:35], 0, v[48:49]
	v_lshl_add_u64 v[48:49], v[68:69], 0, v[44:45]
	s_cmp_eq_u64 vcc, s[100:101]
	s_cbranch_scc1 .Lrow_keep_1
	s_mov_b64 s[100:101], vcc
	v_lshl_add_u64 v[102:103], v[48:49], 0, s[44:45]
	flat_load_dwordx4 v[208:211], v[102:103]
	flat_load_dwordx4 v[212:215], v[48:49]
	flat_load_dwordx4 v[216:219], v[102:103] offset:1024
	flat_load_dwordx4 v[220:223], v[48:49] offset:1024
	flat_load_dwordx4 v[224:227], v[102:103] offset:2048
	flat_load_dwordx4 v[228:231], v[48:49] offset:2048
	flat_load_dwordx4 v[232:235], v[102:103] offset:3072
	flat_load_dwordx4 v[236:239], v[48:49] offset:3072
.Lrow_keep_1:
	global_load_dwordx2 v[68:69], v[50:51], off nt
	global_load_dwordx2 v[70:71], v[50:51], off offset:512 nt
	global_load_dwordx2 v[72:73], v[50:51], off offset:1024 nt
	global_load_dwordx2 v[74:75], v[50:51], off offset:1536 nt
	flat_load_dwordx2 v[76:77], v[46:47] nt
	flat_load_dwordx2 v[78:79], v[46:47] offset:512 nt
	flat_load_dwordx2 v[80:81], v[46:47] offset:1024 nt
	flat_load_dwordx2 v[82:83], v[46:47] offset:1536 nt
	v_add_co_u32_e32 v84, vcc, s1, v48
	v_add_u32_e32 v32, s70, v32
	s_nop 0
	v_addc_co_u32_e32 v85, vcc, 0, v49, vcc
	s_waitcnt vmcnt(0)
	v_cvt_f32_f16_e32 v86, v68
	v_cvt_f32_f16_sdwa v87, v68 dst_sel:DWORD dst_unused:UNUSED_PAD src0_sel:WORD_1
	v_cvt_f32_f16_e32 v68, v69
	v_cvt_f32_f16_sdwa v69, v69 dst_sel:DWORD dst_unused:UNUSED_PAD src0_sel:WORD_1
	s_waitcnt lgkmcnt(0)
; DI float bf_lo(unsigned u) { return __uint_as_float(u << 16); }
; DI float bf_hi(unsigned u) { return __uint_as_float(u & 0xffff0000u); }
; DI f32x4 h4_to_f4(u32x2 t) { const h16x4 h = __builtin_bit_cast(h16x4, t); return (f32x4){(float)h[0], (float)h[1], (float)h[2], (float)h[3]}; }
; DI void phase_row(const Params& P, const void* xs, int sh, void* xd, int dh, int ln, int gl, int gidx, float wgt, int modl, int shidx, bool dry = false) {
;     ...
;             if (sh) v[j] = h4_to_f4(__builtin_nontemporal_load((const u32x2*)((const unsigned short*)xs + e))); else v[j] = __builtin_nontemporal_load((const f32x4*)((const float*)xs + e)); }
;         if (ln >= 0) {
;             u32x2 fv[4];
; #pragma unroll
;             for (int j = 0; j < 4; ++j) fv[j] = __builtin_nontemporal_load((const u32x2*)(U + (size_t)row * D + 4 * lane + 256 * j));
;             const float* gate = mod + (gl * 2 + b) * 9216 + gidx * 1024;
; #pragma unroll
;             for (int j = 0; j < 4; ++j) { const f32x4 g = (*(const f32x4*)(gate + 4 * lane + 256 * j) + 1.f) * wgt;
;                 const f32x4 f = {bf_lo(fv[j].x), bf_hi(fv[j].x), bf_lo(fv[j].y), bf_hi(fv[j].y)};
;                 v[j] = v[j] * DN_ALPHA + g * f; }
;             float s = 0.f;
; #pragma unroll
;             for (int j = 0; j < 4; ++j) s += (v[j][0] + v[j][1]) + (v[j][2] + v[j][3]);
;             const float mean = wave_sum(s, lane) * (1.f / 1024.f);
;             float q = 0.f;
; #pragma unroll
;             for (int j = 0; j < 4; ++j) { v[j] = v[j] - mean; q += (v[j][0] * v[j][0] + v[j][1] * v[j][1]) + (v[j][2] * v[j][2] + v[j][3] * v[j][3]); }
	v_pk_add_f32 v[54:55], v[54:55], 1.0 op_sel_hi:[1,0]
	v_pk_add_f32 v[52:53], v[52:53], 1.0 op_sel_hi:[1,0]
	v_cvt_f32_f16_e32 v88, v70
	v_cvt_f32_f16_sdwa v89, v70 dst_sel:DWORD dst_unused:UNUSED_PAD src0_sel:WORD_1
	v_cvt_f32_f16_e32 v70, v71
	v_cvt_f32_f16_sdwa v71, v71 dst_sel:DWORD dst_unused:UNUSED_PAD src0_sel:WORD_1
	v_pk_add_f32 v[58:59], v[58:59], 1.0 op_sel_hi:[1,0]
	v_pk_add_f32 v[56:57], v[56:57], 1.0 op_sel_hi:[1,0]
	v_cvt_f32_f16_e32 v90, v72
	v_cvt_f32_f16_sdwa v91, v72 dst_sel:DWORD dst_unused:UNUSED_PAD src0_sel:WORD_1
	v_cvt_f32_f16_e32 v72, v73
	v_cvt_f32_f16_sdwa v73, v73 dst_sel:DWORD dst_unused:UNUSED_PAD src0_sel:WORD_1
	v_lshlrev_b32_e32 v94, 16, v76
	v_and_b32_e32 v95, 0xffff0000, v76
	v_lshlrev_b32_e32 v76, 16, v77
	v_and_b32_e32 v77, 0xffff0000, v77
	v_pk_mul_f32 v[54:55], v[54:55], 0.5 op_sel_hi:[1,0]
	v_pk_mul_f32 v[52:53], v[52:53], 0.5 op_sel_hi:[1,0]
	v_pk_add_f32 v[62:63], v[62:63], 1.0 op_sel_hi:[1,0]
	v_pk_add_f32 v[60:61], v[60:61], 1.0 op_sel_hi:[1,0]
	v_cvt_f32_f16_e32 v92, v74
	v_cvt_f32_f16_sdwa v93, v74 dst_sel:DWORD dst_unused:UNUSED_PAD src0_sel:WORD_1
	v_cvt_f32_f16_e32 v74, v75
	v_cvt_f32_f16_sdwa v75, v75 dst_sel:DWORD dst_unused:UNUSED_PAD src0_sel:WORD_1
	v_lshlrev_b32_e32 v96, 16, v78
	v_and_b32_e32 v97, 0xffff0000, v78
	v_lshlrev_b32_e32 v78, 16, v79
	v_and_b32_e32 v79, 0xffff0000, v79
	v_pk_mul_f32 v[58:59], v[58:59], 0.5 op_sel_hi:[1,0]
	v_pk_mul_f32 v[56:57], v[56:57], 0.5 op_sel_hi:[1,0]
	v_pk_mul_f32 v[54:55], v[54:55], v[76:77]
	v_pk_mul_f32 v[52:53], v[52:53], v[94:95]
	v_pk_add_f32 v[66:67], v[66:67], 1.0 op_sel_hi:[1,0]
	v_pk_add_f32 v[64:65], v[64:65], 1.0 op_sel_hi:[1,0]
	v_lshlrev_b32_e32 v98, 16, v80
	v_and_b32_e32 v99, 0xffff0000, v80
	v_lshlrev_b32_e32 v80, 16, v81
	v_and_b32_e32 v81, 0xffff0000, v81
	v_pk_mul_f32 v[62:63], v[62:63], 0.5 op_sel_hi:[1,0]
	v_pk_mul_f32 v[60:61], v[60:61], 0.5 op_sel_hi:[1,0]
	v_pk_mul_f32 v[58:59], v[58:59], v[78:79]
	v_pk_mul_f32 v[56:57], v[56:57], v[96:97]
	v_pk_fma_f32 v[54:55], v[68:69], s[42:43], v[54:55] op_sel_hi:[1,0,1]
	v_pk_fma_f32 v[52:53], v[86:87], s[42:43], v[52:53] op_sel_hi:[1,0,1]
	v_lshlrev_b32_e32 v100, 16, v82
	v_and_b32_e32 v101, 0xffff0000, v82
	v_lshlrev_b32_e32 v82, 16, v83
	v_and_b32_e32 v83, 0xffff0000, v83
	v_pk_mul_f32 v[66:67], v[66:67], 0.5 op_sel_hi:[1,0]
	v_pk_mul_f32 v[64:65], v[64:65], 0.5 op_sel_hi:[1,0]
	v_pk_mul_f32 v[62:63], v[62:63], v[80:81]
	v_pk_mul_f32 v[60:61], v[60:61], v[98:99]
	v_pk_fma_f32 v[58:59], v[70:71], s[42:43], v[58:59] op_sel_hi:[1,0,1]
	v_pk_fma_f32 v[56:57], v[88:89], s[42:43], v[56:57] op_sel_hi:[1,0,1]
	v_add_f32_e32 v33, v52, v53
	v_add_f32_e32 v45, v54, v55
	v_pk_mul_f32 v[66:67], v[66:67], v[82:83]
	v_pk_mul_f32 v[64:65], v[64:65], v[100:101]
	v_pk_fma_f32 v[62:63], v[72:73], s[42:43], v[62:63] op_sel_hi:[1,0,1]
	v_pk_fma_f32 v[60:61], v[90:91], s[42:43], v[60:61] op_sel_hi:[1,0,1]
	v_add_f32_e32 v68, v56, v57
	v_add_f32_e32 v69, v58, v59
	v_add_f32_e32 v33, v33, v45
	v_pk_fma_f32 v[66:67], v[74:75], s[42:43], v[66:67] op_sel_hi:[1,0,1]
	v_pk_fma_f32 v[64:65], v[92:93], s[42:43], v[64:65] op_sel_hi:[1,0,1]
	v_add_f32_e32 v70, v60, v61
	v_add_f32_e32 v71, v62, v63
	v_add_f32_e32 v45, v68, v69
	v_add_f32_e32 v33, 0, v33
	v_add_f32_e32 v72, v64, v65
	v_add_f32_e32 v73, v66, v67
	v_add_f32_e32 v68, v70, v71
	v_add_f32_e32 v33, v33, v45
	v_add_f32_e32 v69, v72, v73
	v_add_f32_e32 v33, v33, v68
	v_add_f32_e32 v33, v33, v69
	s_nop 1
	v_add_f32_dpp v33, v33, v33 quad_perm:[1,0,3,2] row_mask:0xf bank_mask:0xf bound_ctrl:1
	s_nop 1
	v_add_f32_dpp v33, v33, v33 quad_perm:[2,3,0,1] row_mask:0xf bank_mask:0xf bound_ctrl:1
	s_nop 1
	v_add_f32_dpp v33, v33, v33 row_half_mirror row_mask:0xf bank_mask:0xf bound_ctrl:1
	s_nop 1
	v_add_f32_dpp v33, v33, v33 row_mirror row_mask:0xf bank_mask:0xf bound_ctrl:1
	v_mov_b32_e32 v45, v33
	s_nop 1
	v_permlane16_swap_b32_e32 v33, v45
	v_add_f32_e32 v33, v33, v45
	v_mov_b32_e32 v45, v33
	s_nop 1
	v_permlane32_swap_b32_e32 v33, v45
	v_add_f32_e32 v33, v33, v45
	v_fmac_f32_e32 v55, 0xba800000, v33
	v_fmac_f32_e32 v53, 0xba800000, v33
	v_fmac_f32_e32 v59, 0xba800000, v33
	v_fmac_f32_e32 v57, 0xba800000, v33
	v_fmamk_f32 v54, v33, 0xba800000, v54
	v_fmamk_f32 v52, v33, 0xba800000, v52
	v_fmamk_f32 v58, v33, 0xba800000, v58
	v_fmamk_f32 v56, v33, 0xba800000, v56
	v_fmamk_f32 v62, v33, 0xba800000, v62
	v_fmac_f32_e32 v63, 0xba800000, v33
	v_fmamk_f32 v60, v33, 0xba800000, v60
	v_fmac_f32_e32 v61, 0xba800000, v33
	v_fmamk_f32 v66, v33, 0xba800000, v66
; DI unsigned pk_bf16(float lo, float hi) { unsigned r; asm("v_cvt_pk_bf16_f32 %0, %1, %2" : "=v"(r) : "v"(lo), "v"(hi)); return r; }
; DI void phase_row(const Params& P, const void* xs, int sh, void* xd, int dh, int ln, int gl, int gidx, float wgt, int modl, int shidx, bool dry = false) {
;     ...
;             for (int j = 0; j < 4; ++j) { v[j] = v[j] - mean; q += (v[j][0] * v[j][0] + v[j][1] * v[j][1]) + (v[j][2] * v[j][2] + v[j][3] * v[j][3]); }
;             const float rstd = rsqrtf(wave_sum(q, lane) * (1.f / 1024.f) + LN_EPS);
; #pragma unroll
;             for (int j = 0; j < 4; ++j) { const f32x4 g = *(const f32x4*)(P.ln_g + ln * D + 4 * lane + 256 * j), bb = *(const f32x4*)(P.ln_b + ln * D + 4 * lane + 256 * j); v[j] = v[j] * rstd * g + bb; }
;             if (dry) { if (v[0][0] + v[1][1] + v[2][2] + v[3][3] == 12345.678f) P.xbuf[row] = 0.f; continue; }
; #pragma unroll
;             for (int j = 0; j < 4; ++j) { const size_t e = (size_t)row * D + 4 * lane + 256 * j;
;                 if (dh) __builtin_nontemporal_store(f4_to_h4(v[j]), (u32x2*)((unsigned short*)xd + e)); else __builtin_nontemporal_store(v[j], (f32x4*)((float*)xd + e)); }
;         }
;         if (modl >= 0) {
;             const float* shp = mod + (modl * 2 + b) * 9216 + shidx * 1024; const float* sc = shp + 1024;
; #pragma unroll
;             for (int j = 0; j < 4; ++j) { const f32x4 s4 = *(const f32x4*)(shp + 4 * lane + 256 * j), c4 = *(const f32x4*)(sc + 4 * lane + 256 * j);
;                 const f32x4 u = v[j] * (c4 + 1.f) + s4; u32x2 o; o.x = pk_bf16(u[0], u[1]); o.y = pk_bf16(u[2], u[3]);
;                 *(u32x2*)(U + (size_t)row * D + 4 * lane + 256 * j) = o; }
	v_fmac_f32_e32 v67, 0xba800000, v33
	v_fmamk_f32 v64, v33, 0xba800000, v64
	v_fmac_f32_e32 v65, 0xba800000, v33
	v_mul_f32_e32 v33, v53, v53
	v_mul_f32_e32 v45, v55, v55
	v_mul_f32_e32 v68, v57, v57
	v_mul_f32_e32 v69, v59, v59
	v_mul_f32_e32 v70, v61, v61
	v_mul_f32_e32 v71, v63, v63
	v_fmac_f32_e32 v33, v52, v52
	v_fmac_f32_e32 v45, v54, v54
	v_fmac_f32_e32 v68, v56, v56
	v_fmac_f32_e32 v69, v58, v58
	v_mul_f32_e32 v72, v65, v65
	v_mul_f32_e32 v73, v67, v67
	v_fmac_f32_e32 v70, v60, v60
	v_fmac_f32_e32 v71, v62, v62
	v_add_f32_e32 v33, v33, v45
	v_add_f32_e32 v45, v68, v69
	v_fmac_f32_e32 v72, v64, v64
	v_fmac_f32_e32 v73, v66, v66
	v_add_f32_e32 v68, v70, v71
	v_add_f32_e32 v33, v33, v45
	v_add_f32_e32 v69, v72, v73
	v_add_f32_e32 v33, v68, v33
	v_add_f32_e32 v33, v69, v33
	s_nop 1
	v_add_f32_dpp v33, v33, v33 quad_perm:[1,0,3,2] row_mask:0xf bank_mask:0xf bound_ctrl:1
	s_nop 1
	v_add_f32_dpp v33, v33, v33 quad_perm:[2,3,0,1] row_mask:0xf bank_mask:0xf bound_ctrl:1
	s_nop 1
	v_add_f32_dpp v33, v33, v33 row_half_mirror row_mask:0xf bank_mask:0xf bound_ctrl:1
	s_nop 1
	v_add_f32_dpp v33, v33, v33 row_mirror row_mask:0xf bank_mask:0xf bound_ctrl:1
	v_mov_b32_e32 v45, v33
	s_nop 1
	v_permlane16_swap_b32_e32 v33, v45
	v_add_f32_e32 v33, v33, v45
	v_mov_b32_e32 v45, v33
	s_nop 1
	v_permlane32_swap_b32_e32 v33, v45
	v_add_f32_e32 v33, v33, v45
	v_fmamk_f32 v33, v33, 0x3a800000, v198
	v_mul_f32_e32 v45, 0x4b800000, v33
	v_cmp_gt_f32_e32 vcc, s25, v33
	s_nop 1
	v_cndmask_b32_e32 v33, v33, v45, vcc
	v_rsq_f32_e32 v33, v33
	s_nop 0
	v_mul_f32_e32 v45, 0x45800000, v33
	v_cndmask_b32_e32 v68, v33, v45, vcc
	v_pk_mul_f32 v[54:55], v[54:55], v[68:69] op_sel_hi:[1,0]
	v_pk_mul_f32 v[52:53], v[52:53], v[68:69] op_sel_hi:[1,0]
	v_pk_mul_f32 v[56:57], v[56:57], v[68:69] op_sel_hi:[1,0]
	v_pk_mul_f32 v[58:59], v[58:59], v[68:69] op_sel_hi:[1,0]
	v_pk_mul_f32 v[60:61], v[60:61], v[68:69] op_sel_hi:[1,0]
	v_pk_mul_f32 v[62:63], v[62:63], v[68:69] op_sel_hi:[1,0]
	v_pk_mul_f32 v[64:65], v[64:65], v[68:69] op_sel_hi:[1,0]
	v_pk_mul_f32 v[66:67], v[66:67], v[68:69] op_sel_hi:[1,0]
	v_pk_fma_f32 v[8:9], v[112:113], v[52:53], v[128:129]
	v_pk_fma_f32 v[10:11], v[114:115], v[54:55], v[130:131]
	v_pk_fma_f32 v[18:19], v[106:107], v[58:59], v[122:123]
	v_pk_fma_f32 v[16:17], v[104:105], v[56:57], v[120:121]
	v_pk_fma_f32 v[14:15], v[118:119], v[62:63], v[134:135]
	v_pk_fma_f32 v[12:13], v[116:117], v[60:61], v[132:133]
	v_pk_fma_f32 v[22:23], v[110:111], v[66:67], v[126:127]
	v_pk_fma_f32 v[20:21], v[108:109], v[64:65], v[124:125]
	v_cvt_pk_f16_f32 v1, v10, v11
	v_cvt_pk_f16_f32 v0, v8, v9
	v_cvt_pk_f16_f32 v3, v18, v19
	v_cvt_pk_f16_f32 v2, v16, v17
	v_cvt_pk_f16_f32 v5, v14, v15
	v_cvt_pk_f16_f32 v4, v12, v13
	v_cvt_pk_f16_f32 v7, v22, v23
	v_cvt_pk_f16_f32 v6, v20, v21
	global_store_dwordx2 v[50:51], v[0:1], off nt
	global_store_dwordx2 v[50:51], v[2:3], off offset:512 nt
	global_store_dwordx2 v[50:51], v[4:5], off offset:1024 nt
	global_store_dwordx2 v[50:51], v[6:7], off offset:1536 nt
	v_lshl_add_u64 v[24:25], v[48:49], 0, s[44:45]
	v_cmp_lt_i32_e32 vcc, s20, v32
	s_or_b64 s[40:41], vcc, s[40:41]
	v_pk_add_f32 v[0:1], v[208:209], 1.0 op_sel_hi:[1,0]
	v_pk_add_f32 v[2:3], v[210:211], 1.0 op_sel_hi:[1,0]
	v_pk_fma_f32 v[0:1], v[8:9], v[0:1], v[212:213]
	v_pk_fma_f32 v[2:3], v[10:11], v[2:3], v[214:215]
	v_cvt_pk_bf16_f32 v0, v0, v1
	s_nop 0
	v_cvt_pk_bf16_f32 v1, v2, v3
	flat_store_dwordx2 v[46:47], v[0:1]
	v_pk_add_f32 v[0:1], v[216:217], 1.0 op_sel_hi:[1,0]
	v_pk_add_f32 v[2:3], v[218:219], 1.0 op_sel_hi:[1,0]
	v_pk_fma_f32 v[0:1], v[16:17], v[0:1], v[220:221]
	v_pk_fma_f32 v[2:3], v[18:19], v[2:3], v[222:223]
	v_cvt_pk_bf16_f32 v0, v0, v1
	s_nop 0
	v_cvt_pk_bf16_f32 v1, v2, v3
	flat_store_dwordx2 v[46:47], v[0:1] offset:512
	v_pk_add_f32 v[0:1], v[224:225], 1.0 op_sel_hi:[1,0]
	v_pk_add_f32 v[2:3], v[226:227], 1.0 op_sel_hi:[1,0]
	v_pk_fma_f32 v[0:1], v[12:13], v[0:1], v[228:229]
	v_pk_fma_f32 v[2:3], v[14:15], v[2:3], v[230:231]
	v_cvt_pk_bf16_f32 v0, v0, v1
	s_nop 0
	v_cvt_pk_bf16_f32 v1, v2, v3
	flat_store_dwordx2 v[46:47], v[0:1] offset:1024
	v_pk_add_f32 v[0:1], v[232:233], 1.0 op_sel_hi:[1,0]
	v_pk_add_f32 v[2:3], v[234:235], 1.0 op_sel_hi:[1,0]
	v_pk_fma_f32 v[0:1], v[20:21], v[0:1], v[236:237]
	v_pk_fma_f32 v[2:3], v[22:23], v[2:3], v[238:239]
	v_cvt_pk_bf16_f32 v0, v0, v1
	s_nop 0
	v_cvt_pk_bf16_f32 v1, v2, v3
	flat_store_dwordx2 v[46:47], v[0:1] offset:1536
	s_andn2_b64 exec, exec, s[40:41]
	s_cbranch_execnz .LBB0_99

; DI int obid() { int b = blockIdx.x; asm volatile("" : "+s"(b)); return b; }
; DI f32x4 h4_to_f4(u32x2 t) { const h16x4 h = __builtin_bit_cast(h16x4, t); return (f32x4){(float)h[0], (float)h[1], (float)h[2], (float)h[3]}; }
; DI void phase_row(const Params& P, const void* xs, int sh, void* xd, int dh, int ln, int gl, int gidx, float wgt, int modl, int shidx, bool dry = false) {
;     ...
;     for (int row = obid() * 8 + w; row < T; row += gridDim.x * 8) {
;         const int b = row >= SEQ;
;         f32x4 v[4];
; #pragma unroll
;         for (int j = 0; j < 4; ++j) { const size_t e = (size_t)row * D + 4 * lane + 256 * j;
;             if (sh) v[j] = h4_to_f4(__builtin_nontemporal_load((const u32x2*)((const unsigned short*)xs + e))); else v[j] = __builtin_nontemporal_load((const f32x4*)((const float*)xs + e)); }
;         if (ln >= 0) {
;             u32x2 fv[4];
; #pragma unroll
;             for (int j = 0; j < 4; ++j) fv[j] = __builtin_nontemporal_load((const u32x2*)(U + (size_t)row * D + 4 * lane + 256 * j));
;             const float* gate = mod + (gl * 2 + b) * 9216 + gidx * 1024;
; #pragma unroll
;             for (int j = 0; j < 4; ++j) { const f32x4 g = (*(const f32x4*)(gate + 4 * lane + 256 * j) + 1.f) * wgt;
;     ...
;             const float* shp = mod + (modl * 2 + b) * 9216 + shidx * 1024; const float* sc = shp + 1024;
; #pragma unroll
;             for (int j = 0; j < 4; ++j) { const f32x4 s4 = *(const f32x4*)(shp + 4 * lane + 256 * j), c4 = *(const f32x4*)(sc + 4 * lane + 256 * j);
.LBB0_102:
	s_and_b64 vcc, exec, s[2:3]
	s_cbranch_vccz .LBB0_116
	v_readlane_b32 s2, v245, 33
	s_cmp_gt_i32 s2, 13
	s_mov_b64 s[2:3], -1
	s_cbranch_scc0 .LBB0_110
	v_readlane_b32 s2, v245, 33
	s_cmp_eq_u32 s2, 14
	s_mov_b64 s[48:49], -1
	s_cbranch_scc0 .LBB0_109
	s_waitcnt vmcnt(0)
	v_mov_b32_e32 v0, v195
	s_load_dwordx8 s[40:47], s[84:85], 0xc8
	v_ashrrev_i32_e32 v1, 6, v0
	s_mov_b32 s2, s28
	s_waitcnt lgkmcnt(0)
	s_mov_b64 s[26:27], s[46:47]
	s_mov_b64 s[40:41], s[46:47]
	s_nop 0
	v_lshl_add_u32 v32, s2, 3, v1
	v_cmp_gt_i32_e32 vcc, s75, v32
	s_and_saveexec_b64 s[2:3], vcc
	s_mov_b32 s42, 0x3fb504f3
	s_mov_b64 s[44:45], 0x1000
	s_cbranch_execz .LBB0_108
	v_lshlrev_b32_e32 v0, 2, v0
	v_and_b32_e32 v0, 0xfc, v0
	s_load_dwordx16 s[48:63], s[84:85], 0x0
	v_lshlrev_b32_e32 v184, 1, v0
	s_waitcnt lgkmcnt(0)
	s_load_dwordx8 s[48:55], s[84:85], 0xc8
	v_lshl_add_u64 v[2:3], s[40:41], 0, v[184:185]
	s_mov_b64 s[36:37], 0x5808000
	s_add_u32 s30, s26, 0x5580000
	v_lshl_add_u64 v[34:35], v[2:3], 0, s[36:37]
	v_lshlrev_b32_e32 v2, 2, v0
	v_mov_b32_e32 v3, v185
	s_addc_u32 s31, s27, 0
	v_lshl_add_u64 v[4:5], s[26:27], 0, v[2:3]
	s_mov_b64 s[26:27], 0x5588000
	v_lshl_add_u64 v[36:37], v[4:5], 0, s[26:27]
	v_lshl_add_u64 v[4:5], s[62:63], 0, v[2:3]
	s_mov_b64 s[26:27], 0x2000
	v_lshl_add_u64 v[2:3], s[4:5], 0, v[2:3]
	s_mov_b64 s[60:61], 0
	v_lshl_add_u64 v[38:39], v[4:5], 0, s[26:27]
	v_lshl_add_u64 v[40:41], v[2:3], 0, s[26:27]
	s_waitcnt lgkmcnt(0)
	v_lshl_add_u64 v[42:43], s[52:53], 0, v[184:185]
	s_mov_b64 s[40:41], 0
	v_lshlrev_b32_e32 v44, 2, v0
	global_load_dwordx4 v[112:115], v[38:39], off
	global_load_dwordx4 v[104:107], v[38:39], off offset:1024
	global_load_dwordx4 v[128:131], v[40:41], off
	global_load_dwordx4 v[120:123], v[40:41], off offset:1024
	global_load_dwordx4 v[116:119], v[38:39], off offset:2048
	global_load_dwordx4 v[108:111], v[38:39], off offset:3072
	global_load_dwordx4 v[132:135], v[40:41], off offset:2048
	global_load_dwordx4 v[124:127], v[40:41], off offset:3072
	v_mov_b32_e32 v184, 0
	v_lshl_add_u64 v[102:103], v[36:37], 0, v[184:185]
	flat_load_dwordx4 v[136:139], v[102:103]
	flat_load_dwordx4 v[140:143], v[102:103] offset:1024
	flat_load_dwordx4 v[144:147], v[102:103] offset:2048
	flat_load_dwordx4 v[148:151], v[102:103] offset:3072
	v_mov_b32_e32 v184, v203
	v_lshl_add_u64 v[102:103], v[36:37], 0, v[184:185]
	flat_load_dwordx4 v[152:155], v[102:103]
	flat_load_dwordx4 v[156:159], v[102:103] offset:1024
	flat_load_dwordx4 v[160:163], v[102:103] offset:2048
	flat_load_dwordx4 v[164:167], v[102:103] offset:3072
	s_waitcnt vmcnt(0) lgkmcnt(0)
	s_mov_b64 s[100:101], 1
.LBB0_107:
	v_cmp_lt_i32_e32 vcc, s23, v32
	v_ashrrev_i32_e32 v33, 31, v32
	v_lshlrev_b64 v[48:49], 11, v[32:33]
	v_cndmask_b32_e32 v184, 0, v203, vcc
	v_lshl_add_u64 v[46:47], v[36:37], 0, v[184:185]
	v_cndmask_b32_e32 v52, v136, v152, vcc
	v_cndmask_b32_e32 v53, v137, v153, vcc
	v_cndmask_b32_e32 v54, v138, v154, vcc
	v_cndmask_b32_e32 v55, v139, v155, vcc
	v_cndmask_b32_e32 v56, v140, v156, vcc
	v_cndmask_b32_e32 v57, v141, v157, vcc
	v_cndmask_b32_e32 v58, v142, v158, vcc
	v_cndmask_b32_e32 v59, v143, v159, vcc
	v_cndmask_b32_e32 v60, v144, v160, vcc
	v_cndmask_b32_e32 v61, v145, v161, vcc
	v_cndmask_b32_e32 v62, v146, v162, vcc
	v_cndmask_b32_e32 v63, v147, v163, vcc
	v_cndmask_b32_e32 v64, v148, v164, vcc
	v_cndmask_b32_e32 v65, v149, v165, vcc
	v_cndmask_b32_e32 v66, v150, v166, vcc
	v_cndmask_b32_e32 v67, v151, v167, vcc
	v_lshl_add_u64 v[50:51], v[42:43], 0, v[48:49]
	v_lshl_add_u64 v[46:47], v[34:35], 0, v[48:49]
	global_load_dwordx2 v[68:69], v[50:51], off nt
	global_load_dwordx2 v[70:71], v[50:51], off offset:512 nt
	global_load_dwordx2 v[72:73], v[50:51], off offset:1024 nt
	global_load_dwordx2 v[74:75], v[50:51], off offset:1536 nt
	flat_load_dwordx2 v[76:77], v[46:47] nt
	flat_load_dwordx2 v[78:79], v[46:47] offset:512 nt
	flat_load_dwordx2 v[80:81], v[46:47] offset:1024 nt
	flat_load_dwordx2 v[82:83], v[46:47] offset:1536 nt
	v_cndmask_b32_e32 v184, v196, v197, vcc
	v_mov_b32_e32 v45, v185
	v_lshl_add_u64 v[48:49], s[30:31], 0, v[184:185]
	v_lshl_add_u64 v[48:49], v[48:49], 0, v[44:45]
	s_cmp_eq_u64 vcc, s[100:101]
	s_cbranch_scc1 .Lrow_keep_2
	s_mov_b64 s[100:101], vcc
	v_lshl_add_u64 v[102:103], v[48:49], 0, s[44:45]
	flat_load_dwordx4 v[208:211], v[102:103]
	flat_load_dwordx4 v[212:215], v[48:49]
	flat_load_dwordx4 v[216:219], v[102:103] offset:1024
	flat_load_dwordx4 v[220:223], v[48:49] offset:1024
	flat_load_dwordx4 v[224:227], v[102:103] offset:2048
	flat_load_dwordx4 v[228:231], v[48:49] offset:2048
	flat_load_dwordx4 v[232:235], v[102:103] offset:3072
	flat_load_dwordx4 v[236:239], v[48:49] offset:3072
; DI float bf_lo(unsigned u) { return __uint_as_float(u << 16); }
; DI float bf_hi(unsigned u) { return __uint_as_float(u & 0xffff0000u); }
; DI f32x4 h4_to_f4(u32x2 t) { const h16x4 h = __builtin_bit_cast(h16x4, t); return (f32x4){(float)h[0], (float)h[1], (float)h[2], (float)h[3]}; }
; DI void phase_row(const Params& P, const void* xs, int sh, void* xd, int dh, int ln, int gl, int gidx, float wgt, int modl, int shidx, bool dry = false) {
;     ...
;             if (sh) v[j] = h4_to_f4(__builtin_nontemporal_load((const u32x2*)((const unsigned short*)xs + e))); else v[j] = __builtin_nontemporal_load((const f32x4*)((const float*)xs + e)); }
;         if (ln >= 0) {
;             u32x2 fv[4];
; #pragma unroll
;             for (int j = 0; j < 4; ++j) fv[j] = __builtin_nontemporal_load((const u32x2*)(U + (size_t)row * D + 4 * lane + 256 * j));
;             const float* gate = mod + (gl * 2 + b) * 9216 + gidx * 1024;
; #pragma unroll
;             for (int j = 0; j < 4; ++j) { const f32x4 g = (*(const f32x4*)(gate + 4 * lane + 256 * j) + 1.f) * wgt;
;                 const f32x4 f = {bf_lo(fv[j].x), bf_hi(fv[j].x), bf_lo(fv[j].y), bf_hi(fv[j].y)};
;                 v[j] = v[j] * DN_ALPHA + g * f; }
;             float s = 0.f;
; #pragma unroll
;             for (int j = 0; j < 4; ++j) s += (v[j][0] + v[j][1]) + (v[j][2] + v[j][3]);
;             const float mean = wave_sum(s, lane) * (1.f / 1024.f);
;             float q = 0.f;
; #pragma unroll
;             for (int j = 0; j < 4; ++j) { v[j] = v[j] - mean; q += (v[j][0] * v[j][0] + v[j][1] * v[j][1]) + (v[j][2] * v[j][2] + v[j][3] * v[j][3]); }
.Lrow_keep_2:
	v_add_co_u32_e32 v84, vcc, s1, v48
	v_add_u32_e32 v32, s70, v32
	s_nop 0
	v_addc_co_u32_e32 v85, vcc, 0, v49, vcc
	s_waitcnt vmcnt(0)
	v_cvt_f32_f16_e32 v86, v68
	v_cvt_f32_f16_sdwa v87, v68 dst_sel:DWORD dst_unused:UNUSED_PAD src0_sel:WORD_1
	v_cvt_f32_f16_e32 v68, v69
	v_cvt_f32_f16_sdwa v69, v69 dst_sel:DWORD dst_unused:UNUSED_PAD src0_sel:WORD_1
	s_waitcnt lgkmcnt(0)
	v_pk_add_f32 v[54:55], v[54:55], 1.0 op_sel_hi:[1,0]
	v_pk_add_f32 v[52:53], v[52:53], 1.0 op_sel_hi:[1,0]
	v_cvt_f32_f16_e32 v88, v70
	v_cvt_f32_f16_sdwa v89, v70 dst_sel:DWORD dst_unused:UNUSED_PAD src0_sel:WORD_1
	v_cvt_f32_f16_e32 v70, v71
	v_cvt_f32_f16_sdwa v71, v71 dst_sel:DWORD dst_unused:UNUSED_PAD src0_sel:WORD_1
	v_pk_add_f32 v[58:59], v[58:59], 1.0 op_sel_hi:[1,0]
	v_pk_add_f32 v[56:57], v[56:57], 1.0 op_sel_hi:[1,0]
	v_cvt_f32_f16_e32 v90, v72
	v_cvt_f32_f16_sdwa v91, v72 dst_sel:DWORD dst_unused:UNUSED_PAD src0_sel:WORD_1
	v_cvt_f32_f16_e32 v72, v73
	v_cvt_f32_f16_sdwa v73, v73 dst_sel:DWORD dst_unused:UNUSED_PAD src0_sel:WORD_1
	v_lshlrev_b32_e32 v94, 16, v76
	v_and_b32_e32 v95, 0xffff0000, v76
	v_lshlrev_b32_e32 v76, 16, v77
	v_and_b32_e32 v77, 0xffff0000, v77
	v_pk_mul_f32 v[54:55], v[54:55], 0.5 op_sel_hi:[1,0]
	v_pk_mul_f32 v[52:53], v[52:53], 0.5 op_sel_hi:[1,0]
	v_pk_add_f32 v[62:63], v[62:63], 1.0 op_sel_hi:[1,0]
	v_pk_add_f32 v[60:61], v[60:61], 1.0 op_sel_hi:[1,0]
	v_cvt_f32_f16_e32 v92, v74
	v_cvt_f32_f16_sdwa v93, v74 dst_sel:DWORD dst_unused:UNUSED_PAD src0_sel:WORD_1
	v_cvt_f32_f16_e32 v74, v75
	v_cvt_f32_f16_sdwa v75, v75 dst_sel:DWORD dst_unused:UNUSED_PAD src0_sel:WORD_1
	v_lshlrev_b32_e32 v96, 16, v78
	v_and_b32_e32 v97, 0xffff0000, v78
	v_lshlrev_b32_e32 v78, 16, v79
	v_and_b32_e32 v79, 0xffff0000, v79
	v_pk_mul_f32 v[58:59], v[58:59], 0.5 op_sel_hi:[1,0]
	v_pk_mul_f32 v[56:57], v[56:57], 0.5 op_sel_hi:[1,0]
	v_pk_mul_f32 v[54:55], v[54:55], v[76:77]
	v_pk_mul_f32 v[52:53], v[52:53], v[94:95]
	v_pk_add_f32 v[66:67], v[66:67], 1.0 op_sel_hi:[1,0]
	v_pk_add_f32 v[64:65], v[64:65], 1.0 op_sel_hi:[1,0]
	v_lshlrev_b32_e32 v98, 16, v80
	v_and_b32_e32 v99, 0xffff0000, v80
	v_lshlrev_b32_e32 v80, 16, v81
	v_and_b32_e32 v81, 0xffff0000, v81
	v_pk_mul_f32 v[62:63], v[62:63], 0.5 op_sel_hi:[1,0]
	v_pk_mul_f32 v[60:61], v[60:61], 0.5 op_sel_hi:[1,0]
	v_pk_mul_f32 v[58:59], v[58:59], v[78:79]
	v_pk_mul_f32 v[56:57], v[56:57], v[96:97]
	v_pk_fma_f32 v[54:55], v[68:69], s[42:43], v[54:55] op_sel_hi:[1,0,1]
	v_pk_fma_f32 v[52:53], v[86:87], s[42:43], v[52:53] op_sel_hi:[1,0,1]
	v_lshlrev_b32_e32 v100, 16, v82
	v_and_b32_e32 v101, 0xffff0000, v82
	v_lshlrev_b32_e32 v82, 16, v83
	v_and_b32_e32 v83, 0xffff0000, v83
	v_pk_mul_f32 v[66:67], v[66:67], 0.5 op_sel_hi:[1,0]
	v_pk_mul_f32 v[64:65], v[64:65], 0.5 op_sel_hi:[1,0]
	v_pk_mul_f32 v[62:63], v[62:63], v[80:81]
	v_pk_mul_f32 v[60:61], v[60:61], v[98:99]
	v_pk_fma_f32 v[58:59], v[70:71], s[42:43], v[58:59] op_sel_hi:[1,0,1]
	v_pk_fma_f32 v[56:57], v[88:89], s[42:43], v[56:57] op_sel_hi:[1,0,1]
	v_add_f32_e32 v33, v52, v53
	v_add_f32_e32 v45, v54, v55
	v_pk_mul_f32 v[66:67], v[66:67], v[82:83]
	v_pk_mul_f32 v[64:65], v[64:65], v[100:101]
	v_pk_fma_f32 v[62:63], v[72:73], s[42:43], v[62:63] op_sel_hi:[1,0,1]
	v_pk_fma_f32 v[60:61], v[90:91], s[42:43], v[60:61] op_sel_hi:[1,0,1]
	v_add_f32_e32 v68, v56, v57
	v_add_f32_e32 v69, v58, v59
	v_add_f32_e32 v33, v33, v45
	v_pk_fma_f32 v[66:67], v[74:75], s[42:43], v[66:67] op_sel_hi:[1,0,1]
	v_pk_fma_f32 v[64:65], v[92:93], s[42:43], v[64:65] op_sel_hi:[1,0,1]
	v_add_f32_e32 v70, v60, v61
	v_add_f32_e32 v71, v62, v63
	v_add_f32_e32 v45, v68, v69
	v_add_f32_e32 v33, 0, v33
	v_add_f32_e32 v72, v64, v65
	v_add_f32_e32 v73, v66, v67
	v_add_f32_e32 v68, v70, v71
	v_add_f32_e32 v33, v33, v45
	v_add_f32_e32 v69, v72, v73
	v_add_f32_e32 v33, v33, v68
	v_add_f32_e32 v33, v33, v69
	s_nop 1
	v_add_f32_dpp v33, v33, v33 quad_perm:[1,0,3,2] row_mask:0xf bank_mask:0xf bound_ctrl:1
	s_nop 1
	v_add_f32_dpp v33, v33, v33 quad_perm:[2,3,0,1] row_mask:0xf bank_mask:0xf bound_ctrl:1
	s_nop 1
	v_add_f32_dpp v33, v33, v33 row_half_mirror row_mask:0xf bank_mask:0xf bound_ctrl:1
	s_nop 1
	v_add_f32_dpp v33, v33, v33 row_mirror row_mask:0xf bank_mask:0xf bound_ctrl:1
	v_mov_b32_e32 v45, v33
	s_nop 1
	v_permlane16_swap_b32_e32 v33, v45
	v_add_f32_e32 v33, v33, v45
	v_mov_b32_e32 v45, v33
	s_nop 1
	v_permlane32_swap_b32_e32 v33, v45
	v_add_f32_e32 v33, v33, v45
	v_fmac_f32_e32 v55, 0xba800000, v33
	v_fmac_f32_e32 v53, 0xba800000, v33
	v_fmac_f32_e32 v59, 0xba800000, v33
	v_fmac_f32_e32 v57, 0xba800000, v33
	v_fmamk_f32 v54, v33, 0xba800000, v54
	v_fmamk_f32 v52, v33, 0xba800000, v52
	v_fmamk_f32 v58, v33, 0xba800000, v58
	v_fmamk_f32 v56, v33, 0xba800000, v56
; DI unsigned pk_bf16(float lo, float hi) { unsigned r; asm("v_cvt_pk_bf16_f32 %0, %1, %2" : "=v"(r) : "v"(lo), "v"(hi)); return r; }
; DI void phase_row(const Params& P, const void* xs, int sh, void* xd, int dh, int ln, int gl, int gidx, float wgt, int modl, int shidx, bool dry = false) {
;     ...
;             for (int j = 0; j < 4; ++j) { v[j] = v[j] - mean; q += (v[j][0] * v[j][0] + v[j][1] * v[j][1]) + (v[j][2] * v[j][2] + v[j][3] * v[j][3]); }
;             const float rstd = rsqrtf(wave_sum(q, lane) * (1.f / 1024.f) + LN_EPS);
; #pragma unroll
;             for (int j = 0; j < 4; ++j) { const f32x4 g = *(const f32x4*)(P.ln_g + ln * D + 4 * lane + 256 * j), bb = *(const f32x4*)(P.ln_b + ln * D + 4 * lane + 256 * j); v[j] = v[j] * rstd * g + bb; }
;             if (dry) { if (v[0][0] + v[1][1] + v[2][2] + v[3][3] == 12345.678f) P.xbuf[row] = 0.f; continue; }
; #pragma unroll
;             for (int j = 0; j < 4; ++j) { const size_t e = (size_t)row * D + 4 * lane + 256 * j;
;                 if (dh) __builtin_nontemporal_store(f4_to_h4(v[j]), (u32x2*)((unsigned short*)xd + e)); else __builtin_nontemporal_store(v[j], (f32x4*)((float*)xd + e)); }
;         }
;         if (modl >= 0) {
;             const float* shp = mod + (modl * 2 + b) * 9216 + shidx * 1024; const float* sc = shp + 1024;
; #pragma unroll
;             for (int j = 0; j < 4; ++j) { const f32x4 s4 = *(const f32x4*)(shp + 4 * lane + 256 * j), c4 = *(const f32x4*)(sc + 4 * lane + 256 * j);
;                 const f32x4 u = v[j] * (c4 + 1.f) + s4; u32x2 o; o.x = pk_bf16(u[0], u[1]); o.y = pk_bf16(u[2], u[3]);
;                 *(u32x2*)(U + (size_t)row * D + 4 * lane + 256 * j) = o; }
	v_fmamk_f32 v62, v33, 0xba800000, v62
	v_fmac_f32_e32 v63, 0xba800000, v33
	v_fmamk_f32 v60, v33, 0xba800000, v60
	v_fmac_f32_e32 v61, 0xba800000, v33
	v_fmamk_f32 v66, v33, 0xba800000, v66
	v_fmac_f32_e32 v67, 0xba800000, v33
	v_fmamk_f32 v64, v33, 0xba800000, v64
	v_fmac_f32_e32 v65, 0xba800000, v33
	v_mul_f32_e32 v33, v53, v53
	v_mul_f32_e32 v45, v55, v55
	v_mul_f32_e32 v68, v57, v57
	v_mul_f32_e32 v69, v59, v59
	v_mul_f32_e32 v70, v61, v61
	v_mul_f32_e32 v71, v63, v63
	v_fmac_f32_e32 v33, v52, v52
	v_fmac_f32_e32 v45, v54, v54
	v_fmac_f32_e32 v68, v56, v56
	v_fmac_f32_e32 v69, v58, v58
	v_mul_f32_e32 v72, v65, v65
	v_mul_f32_e32 v73, v67, v67
	v_fmac_f32_e32 v70, v60, v60
	v_fmac_f32_e32 v71, v62, v62
	v_add_f32_e32 v33, v33, v45
	v_add_f32_e32 v45, v68, v69
	v_fmac_f32_e32 v72, v64, v64
	v_fmac_f32_e32 v73, v66, v66
	v_add_f32_e32 v68, v70, v71
	v_add_f32_e32 v33, v33, v45
	v_add_f32_e32 v69, v72, v73
	v_add_f32_e32 v33, v68, v33
	v_add_f32_e32 v33, v69, v33
	s_nop 1
	v_add_f32_dpp v33, v33, v33 quad_perm:[1,0,3,2] row_mask:0xf bank_mask:0xf bound_ctrl:1
	s_nop 1
	v_add_f32_dpp v33, v33, v33 quad_perm:[2,3,0,1] row_mask:0xf bank_mask:0xf bound_ctrl:1
	s_nop 1
	v_add_f32_dpp v33, v33, v33 row_half_mirror row_mask:0xf bank_mask:0xf bound_ctrl:1
	s_nop 1
	v_add_f32_dpp v33, v33, v33 row_mirror row_mask:0xf bank_mask:0xf bound_ctrl:1
	v_mov_b32_e32 v45, v33
	s_nop 1
	v_permlane16_swap_b32_e32 v33, v45
	v_add_f32_e32 v33, v33, v45
	v_mov_b32_e32 v45, v33
	s_nop 1
	v_permlane32_swap_b32_e32 v33, v45
	v_add_f32_e32 v33, v33, v45
	v_fmamk_f32 v33, v33, 0x3a800000, v198
	v_mul_f32_e32 v45, 0x4b800000, v33
	v_cmp_gt_f32_e32 vcc, s25, v33
	s_nop 1
	v_cndmask_b32_e32 v33, v33, v45, vcc
	v_rsq_f32_e32 v33, v33
	s_nop 0
	v_mul_f32_e32 v45, 0x45800000, v33
	v_cndmask_b32_e32 v68, v33, v45, vcc
	v_pk_mul_f32 v[54:55], v[54:55], v[68:69] op_sel_hi:[1,0]
	v_pk_mul_f32 v[52:53], v[52:53], v[68:69] op_sel_hi:[1,0]
	v_pk_mul_f32 v[56:57], v[56:57], v[68:69] op_sel_hi:[1,0]
	v_pk_mul_f32 v[58:59], v[58:59], v[68:69] op_sel_hi:[1,0]
	v_pk_mul_f32 v[60:61], v[60:61], v[68:69] op_sel_hi:[1,0]
	v_pk_mul_f32 v[62:63], v[62:63], v[68:69] op_sel_hi:[1,0]
	v_pk_mul_f32 v[64:65], v[64:65], v[68:69] op_sel_hi:[1,0]
	v_pk_mul_f32 v[66:67], v[66:67], v[68:69] op_sel_hi:[1,0]
	v_pk_fma_f32 v[8:9], v[112:113], v[52:53], v[128:129]
	v_pk_fma_f32 v[10:11], v[114:115], v[54:55], v[130:131]
	v_pk_fma_f32 v[18:19], v[106:107], v[58:59], v[122:123]
	v_pk_fma_f32 v[16:17], v[104:105], v[56:57], v[120:121]
	v_pk_fma_f32 v[14:15], v[118:119], v[62:63], v[134:135]
	v_pk_fma_f32 v[12:13], v[116:117], v[60:61], v[132:133]
	v_pk_fma_f32 v[22:23], v[110:111], v[66:67], v[126:127]
	v_pk_fma_f32 v[20:21], v[108:109], v[64:65], v[124:125]
	v_cvt_pk_f16_f32 v1, v10, v11
	v_cvt_pk_f16_f32 v0, v8, v9
	v_cvt_pk_f16_f32 v3, v18, v19
	v_cvt_pk_f16_f32 v2, v16, v17
	v_cvt_pk_f16_f32 v5, v14, v15
	v_cvt_pk_f16_f32 v4, v12, v13
	v_cvt_pk_f16_f32 v7, v22, v23
	v_cvt_pk_f16_f32 v6, v20, v21
	global_store_dwordx2 v[50:51], v[0:1], off nt
	global_store_dwordx2 v[50:51], v[2:3], off offset:512 nt
	global_store_dwordx2 v[50:51], v[4:5], off offset:1024 nt
	global_store_dwordx2 v[50:51], v[6:7], off offset:1536 nt
	v_lshl_add_u64 v[24:25], v[48:49], 0, s[44:45]
	v_cmp_lt_i32_e32 vcc, s20, v32
	s_or_b64 s[40:41], vcc, s[40:41]
	v_pk_add_f32 v[0:1], v[208:209], 1.0 op_sel_hi:[1,0]
	v_pk_add_f32 v[2:3], v[210:211], 1.0 op_sel_hi:[1,0]
	v_pk_fma_f32 v[0:1], v[8:9], v[0:1], v[212:213]
	v_pk_fma_f32 v[2:3], v[10:11], v[2:3], v[214:215]
	v_cvt_pk_bf16_f32 v0, v0, v1
	s_nop 0
	v_cvt_pk_bf16_f32 v1, v2, v3
	flat_store_dwordx2 v[46:47], v[0:1]
	v_pk_add_f32 v[0:1], v[216:217], 1.0 op_sel_hi:[1,0]
	v_pk_add_f32 v[2:3], v[218:219], 1.0 op_sel_hi:[1,0]
	v_pk_fma_f32 v[0:1], v[16:17], v[0:1], v[220:221]
	v_pk_fma_f32 v[2:3], v[18:19], v[2:3], v[222:223]
	v_cvt_pk_bf16_f32 v0, v0, v1
	s_nop 0
	v_cvt_pk_bf16_f32 v1, v2, v3
	flat_store_dwordx2 v[46:47], v[0:1] offset:512
	v_pk_add_f32 v[0:1], v[224:225], 1.0 op_sel_hi:[1,0]
	v_pk_add_f32 v[2:3], v[226:227], 1.0 op_sel_hi:[1,0]
	v_pk_fma_f32 v[0:1], v[12:13], v[0:1], v[228:229]
	v_pk_fma_f32 v[2:3], v[14:15], v[2:3], v[230:231]
	v_cvt_pk_bf16_f32 v0, v0, v1
	s_nop 0
	v_cvt_pk_bf16_f32 v1, v2, v3
	flat_store_dwordx2 v[46:47], v[0:1] offset:1024
	v_pk_add_f32 v[0:1], v[232:233], 1.0 op_sel_hi:[1,0]
	v_pk_add_f32 v[2:3], v[234:235], 1.0 op_sel_hi:[1,0]
	v_pk_fma_f32 v[0:1], v[20:21], v[0:1], v[236:237]
	v_pk_fma_f32 v[2:3], v[22:23], v[2:3], v[238:239]
	v_cvt_pk_bf16_f32 v0, v0, v1
	s_nop 0
	v_cvt_pk_bf16_f32 v1, v2, v3
	flat_store_dwordx2 v[46:47], v[0:1] offset:1536
	s_andn2_b64 exec, exec, s[40:41]
	s_cbranch_execnz .LBB0_107

; DI int obid() { int b = blockIdx.x; asm volatile("" : "+s"(b)); return b; }
; DI f32x4 h4_to_f4(u32x2 t) { const h16x4 h = __builtin_bit_cast(h16x4, t); return (f32x4){(float)h[0], (float)h[1], (float)h[2], (float)h[3]}; }
; DI void phase_row(const Params& P, const void* xs, int sh, void* xd, int dh, int ln, int gl, int gidx, float wgt, int modl, int shidx, bool dry = false) {
;     ...
;     for (int row = obid() * 8 + w; row < T; row += gridDim.x * 8) {
;         const int b = row >= SEQ;
;         f32x4 v[4];
; #pragma unroll
;         for (int j = 0; j < 4; ++j) { const size_t e = (size_t)row * D + 4 * lane + 256 * j;
;             if (sh) v[j] = h4_to_f4(__builtin_nontemporal_load((const u32x2*)((const unsigned short*)xs + e))); else v[j] = __builtin_nontemporal_load((const f32x4*)((const float*)xs + e)); }
;         if (ln >= 0) {
;             u32x2 fv[4];
; #pragma unroll
;             for (int j = 0; j < 4; ++j) fv[j] = __builtin_nontemporal_load((const u32x2*)(U + (size_t)row * D + 4 * lane + 256 * j));
;             const float* gate = mod + (gl * 2 + b) * 9216 + gidx * 1024;
; #pragma unroll
;             for (int j = 0; j < 4; ++j) { const f32x4 g = (*(const f32x4*)(gate + 4 * lane + 256 * j) + 1.f) * wgt;
;     ...
;             const float* shp = mod + (modl * 2 + b) * 9216 + shidx * 1024; const float* sc = shp + 1024;
; #pragma unroll
;             for (int j = 0; j < 4; ++j) { const f32x4 s4 = *(const f32x4*)(shp + 4 * lane + 256 * j), c4 = *(const f32x4*)(sc + 4 * lane + 256 * j);
.LBB0_110:
	s_and_b64 vcc, exec, s[2:3]
	s_cbranch_vccz .LBB0_116
	v_readlane_b32 s2, v245, 33
	s_cmp_eq_u32 s2, 11
	s_mov_b64 s[48:49], -1
	s_cbranch_scc0 .LBB0_116
	s_waitcnt vmcnt(0)
	v_mov_b32_e32 v0, v195
	s_load_dwordx8 s[40:47], s[84:85], 0xc8
	v_ashrrev_i32_e32 v1, 6, v0
	s_mov_b32 s2, s28
	s_waitcnt lgkmcnt(0)
	s_mov_b64 s[26:27], s[46:47]
	s_mov_b64 s[30:31], s[46:47]
	s_nop 0
	v_lshl_add_u32 v32, s2, 3, v1
	v_cmp_gt_i32_e32 vcc, s75, v32
	s_and_saveexec_b64 s[2:3], vcc
	s_mov_b32 s42, 0x3fb504f3
	s_mov_b64 s[44:45], 0x1000
	s_cbranch_execz .LBB0_115
	v_lshlrev_b32_e32 v0, 2, v0
	v_and_b32_e32 v0, 0xfc, v0
	s_load_dwordx16 s[48:63], s[84:85], 0x0
	v_lshlrev_b32_e32 v184, 1, v0
	s_waitcnt lgkmcnt(0)
	s_load_dwordx8 s[48:55], s[84:85], 0xc8
	v_lshl_add_u64 v[2:3], s[30:31], 0, v[184:185]
	s_mov_b64 s[30:31], 0x5808000
	v_lshl_add_u64 v[34:35], v[2:3], 0, s[30:31]
	v_lshlrev_b32_e32 v2, 2, v0
	v_mov_b32_e32 v3, v185
	v_lshl_add_u64 v[4:5], s[26:27], 0, v[2:3]
	s_mov_b64 s[30:31], 0x5585000
	v_lshl_add_u64 v[36:37], v[4:5], 0, s[30:31]
	s_add_u32 s30, s26, 0x5586000
	v_lshl_add_u64 v[4:5], s[62:63], 0, v[2:3]
	v_lshl_add_u64 v[2:3], s[4:5], 0, v[2:3]
	s_addc_u32 s31, s27, 0
	s_mov_b64 s[60:61], 0
	v_lshl_add_u64 v[38:39], v[4:5], 0, s[44:45]
	v_lshl_add_u64 v[40:41], v[2:3], 0, s[44:45]
	s_waitcnt lgkmcnt(0)
	v_lshl_add_u64 v[42:43], s[52:53], 0, v[184:185]
	s_mov_b64 s[40:41], 0
	v_lshlrev_b32_e32 v44, 2, v0
	global_load_dwordx4 v[112:115], v[38:39], off
	global_load_dwordx4 v[104:107], v[38:39], off offset:1024
	global_load_dwordx4 v[128:131], v[40:41], off
	global_load_dwordx4 v[120:123], v[40:41], off offset:1024
	global_load_dwordx4 v[116:119], v[38:39], off offset:2048
	global_load_dwordx4 v[108:111], v[38:39], off offset:3072
	global_load_dwordx4 v[132:135], v[40:41], off offset:2048
	global_load_dwordx4 v[124:127], v[40:41], off offset:3072
	v_mov_b32_e32 v184, 0
	v_lshl_add_u64 v[102:103], v[36:37], 0, v[184:185]
	flat_load_dwordx4 v[136:139], v[102:103]
	flat_load_dwordx4 v[140:143], v[102:103] offset:1024
	flat_load_dwordx4 v[144:147], v[102:103] offset:2048
	flat_load_dwordx4 v[148:151], v[102:103] offset:3072
	v_mov_b32_e32 v184, v203
	v_lshl_add_u64 v[102:103], v[36:37], 0, v[184:185]
	flat_load_dwordx4 v[152:155], v[102:103]
	flat_load_dwordx4 v[156:159], v[102:103] offset:1024
	flat_load_dwordx4 v[160:163], v[102:103] offset:2048
	flat_load_dwordx4 v[164:167], v[102:103] offset:3072
	s_waitcnt vmcnt(0) lgkmcnt(0)
	s_mov_b64 s[100:101], 1
.LBB0_114:
	v_cmp_lt_i32_e32 vcc, s23, v32
	v_ashrrev_i32_e32 v33, 31, v32
	v_lshlrev_b64 v[48:49], 11, v[32:33]
	v_cndmask_b32_e32 v184, 0, v203, vcc
	v_mov_b32_e32 v45, v185
	v_lshl_add_u64 v[46:47], v[36:37], 0, v[184:185]
	v_lshl_add_u64 v[68:69], s[30:31], 0, v[184:185]
	v_lshl_add_u64 v[50:51], v[42:43], 0, v[48:49]
	v_cndmask_b32_e32 v52, v136, v152, vcc
	v_cndmask_b32_e32 v53, v137, v153, vcc
	v_cndmask_b32_e32 v54, v138, v154, vcc
	v_cndmask_b32_e32 v55, v139, v155, vcc
	v_cndmask_b32_e32 v56, v140, v156, vcc
	v_cndmask_b32_e32 v57, v141, v157, vcc
	v_cndmask_b32_e32 v58, v142, v158, vcc
	v_cndmask_b32_e32 v59, v143, v159, vcc
	v_cndmask_b32_e32 v60, v144, v160, vcc
	v_cndmask_b32_e32 v61, v145, v161, vcc
	v_cndmask_b32_e32 v62, v146, v162, vcc
	v_cndmask_b32_e32 v63, v147, v163, vcc
	v_cndmask_b32_e32 v64, v148, v164, vcc
	v_cndmask_b32_e32 v65, v149, v165, vcc
	v_cndmask_b32_e32 v66, v150, v166, vcc
	v_cndmask_b32_e32 v67, v151, v167, vcc
	v_lshl_add_u64 v[46:47], v[34:35], 0, v[48:49]
	v_lshl_add_u64 v[48:49], v[68:69], 0, v[44:45]
	s_cmp_eq_u64 vcc, s[100:101]
	s_cbranch_scc1 .Lrow_keep_3
	s_mov_b64 s[100:101], vcc
	v_lshl_add_u64 v[102:103], v[48:49], 0, s[44:45]
	flat_load_dwordx4 v[208:211], v[102:103]
	flat_load_dwordx4 v[212:215], v[48:49]
	flat_load_dwordx4 v[216:219], v[102:103] offset:1024
	flat_load_dwordx4 v[220:223], v[48:49] offset:1024
	flat_load_dwordx4 v[224:227], v[102:103] offset:2048
	flat_load_dwordx4 v[228:231], v[48:49] offset:2048
	flat_load_dwordx4 v[232:235], v[102:103] offset:3072
	flat_load_dwordx4 v[236:239], v[48:49] offset:3072
.Lrow_keep_3:
	global_load_dwordx2 v[68:69], v[50:51], off nt
	global_load_dwordx2 v[70:71], v[50:51], off offset:512 nt
	global_load_dwordx2 v[72:73], v[50:51], off offset:1024 nt
	global_load_dwordx2 v[74:75], v[50:51], off offset:1536 nt
	flat_load_dwordx2 v[76:77], v[46:47] nt
	flat_load_dwordx2 v[78:79], v[46:47] offset:512 nt
	flat_load_dwordx2 v[80:81], v[46:47] offset:1024 nt
	flat_load_dwordx2 v[82:83], v[46:47] offset:1536 nt
	v_add_co_u32_e32 v84, vcc, s1, v48
	v_add_u32_e32 v32, s70, v32
	s_nop 0
	v_addc_co_u32_e32 v85, vcc, 0, v49, vcc
	s_waitcnt vmcnt(0)
	v_cvt_f32_f16_e32 v86, v68
	v_cvt_f32_f16_sdwa v87, v68 dst_sel:DWORD dst_unused:UNUSED_PAD src0_sel:WORD_1
	v_cvt_f32_f16_e32 v68, v69
	v_cvt_f32_f16_sdwa v69, v69 dst_sel:DWORD dst_unused:UNUSED_PAD src0_sel:WORD_1
	v_cvt_f32_f16_e32 v88, v70
	v_cvt_f32_f16_sdwa v89, v70 dst_sel:DWORD dst_unused:UNUSED_PAD src0_sel:WORD_1
	v_cvt_f32_f16_e32 v70, v71
	v_cvt_f32_f16_sdwa v71, v71 dst_sel:DWORD dst_unused:UNUSED_PAD src0_sel:WORD_1
	s_waitcnt lgkmcnt(0)
; DI float bf_lo(unsigned u) { return __uint_as_float(u << 16); }
; DI float bf_hi(unsigned u) { return __uint_as_float(u & 0xffff0000u); }
; DI f32x4 h4_to_f4(u32x2 t) { const h16x4 h = __builtin_bit_cast(h16x4, t); return (f32x4){(float)h[0], (float)h[1], (float)h[2], (float)h[3]}; }
; DI void phase_row(const Params& P, const void* xs, int sh, void* xd, int dh, int ln, int gl, int gidx, float wgt, int modl, int shidx, bool dry = false) {
;     ...
;             if (sh) v[j] = h4_to_f4(__builtin_nontemporal_load((const u32x2*)((const unsigned short*)xs + e))); else v[j] = __builtin_nontemporal_load((const f32x4*)((const float*)xs + e)); }
;         if (ln >= 0) {
;             u32x2 fv[4];
; #pragma unroll
;             for (int j = 0; j < 4; ++j) fv[j] = __builtin_nontemporal_load((const u32x2*)(U + (size_t)row * D + 4 * lane + 256 * j));
;             const float* gate = mod + (gl * 2 + b) * 9216 + gidx * 1024;
; #pragma unroll
;             for (int j = 0; j < 4; ++j) { const f32x4 g = (*(const f32x4*)(gate + 4 * lane + 256 * j) + 1.f) * wgt;
;                 const f32x4 f = {bf_lo(fv[j].x), bf_hi(fv[j].x), bf_lo(fv[j].y), bf_hi(fv[j].y)};
;                 v[j] = v[j] * DN_ALPHA + g * f; }
;             float s = 0.f;
; #pragma unroll
;             for (int j = 0; j < 4; ++j) s += (v[j][0] + v[j][1]) + (v[j][2] + v[j][3]);
;             const float mean = wave_sum(s, lane) * (1.f / 1024.f);
;             float q = 0.f;
; #pragma unroll
;             for (int j = 0; j < 4; ++j) { v[j] = v[j] - mean; q += (v[j][0] * v[j][0] + v[j][1] * v[j][1]) + (v[j][2] * v[j][2] + v[j][3] * v[j][3]); }
	v_pk_add_f32 v[54:55], v[54:55], 1.0 op_sel_hi:[1,0]
	v_pk_add_f32 v[52:53], v[52:53], 1.0 op_sel_hi:[1,0]
	v_cvt_f32_f16_e32 v90, v72
	v_cvt_f32_f16_sdwa v91, v72 dst_sel:DWORD dst_unused:UNUSED_PAD src0_sel:WORD_1
	v_cvt_f32_f16_e32 v72, v73
	v_cvt_f32_f16_sdwa v73, v73 dst_sel:DWORD dst_unused:UNUSED_PAD src0_sel:WORD_1
	v_lshlrev_b32_e32 v94, 16, v76
	v_and_b32_e32 v95, 0xffff0000, v76
	v_lshlrev_b32_e32 v76, 16, v77
	v_and_b32_e32 v77, 0xffff0000, v77
	v_pk_add_f32 v[58:59], v[58:59], 1.0 op_sel_hi:[1,0]
	v_pk_add_f32 v[56:57], v[56:57], 1.0 op_sel_hi:[1,0]
	v_cvt_f32_f16_e32 v92, v74
	v_cvt_f32_f16_sdwa v93, v74 dst_sel:DWORD dst_unused:UNUSED_PAD src0_sel:WORD_1
	v_cvt_f32_f16_e32 v74, v75
	v_cvt_f32_f16_sdwa v75, v75 dst_sel:DWORD dst_unused:UNUSED_PAD src0_sel:WORD_1
	v_lshlrev_b32_e32 v96, 16, v78
	v_and_b32_e32 v97, 0xffff0000, v78
	v_lshlrev_b32_e32 v78, 16, v79
	v_and_b32_e32 v79, 0xffff0000, v79
	v_pk_mul_f32 v[54:55], v[54:55], v[76:77]
	v_pk_mul_f32 v[52:53], v[52:53], v[94:95]
	v_pk_add_f32 v[62:63], v[62:63], 1.0 op_sel_hi:[1,0]
	v_pk_add_f32 v[60:61], v[60:61], 1.0 op_sel_hi:[1,0]
	v_lshlrev_b32_e32 v98, 16, v80
	v_and_b32_e32 v99, 0xffff0000, v80
	v_lshlrev_b32_e32 v80, 16, v81
	v_and_b32_e32 v81, 0xffff0000, v81
	v_pk_mul_f32 v[58:59], v[58:59], v[78:79]
	v_pk_mul_f32 v[56:57], v[56:57], v[96:97]
	v_pk_fma_f32 v[54:55], v[68:69], s[42:43], v[54:55] op_sel_hi:[1,0,1]
	v_pk_fma_f32 v[52:53], v[86:87], s[42:43], v[52:53] op_sel_hi:[1,0,1]
	v_pk_add_f32 v[66:67], v[66:67], 1.0 op_sel_hi:[1,0]
	v_pk_add_f32 v[64:65], v[64:65], 1.0 op_sel_hi:[1,0]
	v_lshlrev_b32_e32 v100, 16, v82
	v_and_b32_e32 v101, 0xffff0000, v82
	v_lshlrev_b32_e32 v82, 16, v83
	v_and_b32_e32 v83, 0xffff0000, v83
	v_pk_mul_f32 v[62:63], v[62:63], v[80:81]
	v_pk_mul_f32 v[60:61], v[60:61], v[98:99]
	v_pk_fma_f32 v[58:59], v[70:71], s[42:43], v[58:59] op_sel_hi:[1,0,1]
	v_pk_fma_f32 v[56:57], v[88:89], s[42:43], v[56:57] op_sel_hi:[1,0,1]
	v_add_f32_e32 v33, v52, v53
	v_add_f32_e32 v45, v54, v55
	v_pk_mul_f32 v[66:67], v[66:67], v[82:83]
	v_pk_mul_f32 v[64:65], v[64:65], v[100:101]
	v_pk_fma_f32 v[62:63], v[72:73], s[42:43], v[62:63] op_sel_hi:[1,0,1]
	v_pk_fma_f32 v[60:61], v[90:91], s[42:43], v[60:61] op_sel_hi:[1,0,1]
	v_add_f32_e32 v68, v56, v57
	v_add_f32_e32 v69, v58, v59
	v_add_f32_e32 v33, v33, v45
	v_pk_fma_f32 v[66:67], v[74:75], s[42:43], v[66:67] op_sel_hi:[1,0,1]
	v_pk_fma_f32 v[64:65], v[92:93], s[42:43], v[64:65] op_sel_hi:[1,0,1]
	v_add_f32_e32 v70, v60, v61
	v_add_f32_e32 v71, v62, v63
	v_add_f32_e32 v45, v68, v69
	v_add_f32_e32 v33, 0, v33
	v_add_f32_e32 v72, v64, v65
	v_add_f32_e32 v73, v66, v67
	v_add_f32_e32 v68, v70, v71
	v_add_f32_e32 v33, v33, v45
	v_add_f32_e32 v69, v72, v73
	v_add_f32_e32 v33, v33, v68
	v_add_f32_e32 v33, v33, v69
	s_nop 1
	v_add_f32_dpp v33, v33, v33 quad_perm:[1,0,3,2] row_mask:0xf bank_mask:0xf bound_ctrl:1
	s_nop 1
	v_add_f32_dpp v33, v33, v33 quad_perm:[2,3,0,1] row_mask:0xf bank_mask:0xf bound_ctrl:1
	s_nop 1
	v_add_f32_dpp v33, v33, v33 row_half_mirror row_mask:0xf bank_mask:0xf bound_ctrl:1
	s_nop 1
	v_add_f32_dpp v33, v33, v33 row_mirror row_mask:0xf bank_mask:0xf bound_ctrl:1
	v_mov_b32_e32 v45, v33
	s_nop 1
	v_permlane16_swap_b32_e32 v33, v45
	v_add_f32_e32 v33, v33, v45
	v_mov_b32_e32 v45, v33
	s_nop 1
	v_permlane32_swap_b32_e32 v33, v45
	v_add_f32_e32 v33, v33, v45
	v_fmac_f32_e32 v55, 0xba800000, v33
	v_fmac_f32_e32 v53, 0xba800000, v33
	v_fmac_f32_e32 v59, 0xba800000, v33
	v_fmac_f32_e32 v57, 0xba800000, v33
	v_fmamk_f32 v54, v33, 0xba800000, v54
	v_fmamk_f32 v52, v33, 0xba800000, v52
	v_fmamk_f32 v58, v33, 0xba800000, v58
	v_fmamk_f32 v56, v33, 0xba800000, v56
	v_fmamk_f32 v62, v33, 0xba800000, v62
	v_fmac_f32_e32 v63, 0xba800000, v33
	v_fmamk_f32 v60, v33, 0xba800000, v60
	v_fmac_f32_e32 v61, 0xba800000, v33
	v_fmamk_f32 v66, v33, 0xba800000, v66
	v_fmac_f32_e32 v67, 0xba800000, v33
	v_fmamk_f32 v64, v33, 0xba800000, v64
	v_fmac_f32_e32 v65, 0xba800000, v33
	v_mul_f32_e32 v33, v53, v53
	v_mul_f32_e32 v45, v55, v55
	v_mul_f32_e32 v68, v57, v57
	v_mul_f32_e32 v69, v59, v59
	v_mul_f32_e32 v70, v61, v61
	v_mul_f32_e32 v71, v63, v63
	v_fmac_f32_e32 v33, v52, v52
; DI unsigned pk_bf16(float lo, float hi) { unsigned r; asm("v_cvt_pk_bf16_f32 %0, %1, %2" : "=v"(r) : "v"(lo), "v"(hi)); return r; }
; DI void phase_row(const Params& P, const void* xs, int sh, void* xd, int dh, int ln, int gl, int gidx, float wgt, int modl, int shidx, bool dry = false) {
;     ...
;             for (int j = 0; j < 4; ++j) { v[j] = v[j] - mean; q += (v[j][0] * v[j][0] + v[j][1] * v[j][1]) + (v[j][2] * v[j][2] + v[j][3] * v[j][3]); }
;             const float rstd = rsqrtf(wave_sum(q, lane) * (1.f / 1024.f) + LN_EPS);
; #pragma unroll
;             for (int j = 0; j < 4; ++j) { const f32x4 g = *(const f32x4*)(P.ln_g + ln * D + 4 * lane + 256 * j), bb = *(const f32x4*)(P.ln_b + ln * D + 4 * lane + 256 * j); v[j] = v[j] * rstd * g + bb; }
;             if (dry) { if (v[0][0] + v[1][1] + v[2][2] + v[3][3] == 12345.678f) P.xbuf[row] = 0.f; continue; }
; #pragma unroll
;             for (int j = 0; j < 4; ++j) { const size_t e = (size_t)row * D + 4 * lane + 256 * j;
;                 if (dh) __builtin_nontemporal_store(f4_to_h4(v[j]), (u32x2*)((unsigned short*)xd + e)); else __builtin_nontemporal_store(v[j], (f32x4*)((float*)xd + e)); }
;         }
;         if (modl >= 0) {
;             const float* shp = mod + (modl * 2 + b) * 9216 + shidx * 1024; const float* sc = shp + 1024;
; #pragma unroll
;             for (int j = 0; j < 4; ++j) { const f32x4 s4 = *(const f32x4*)(shp + 4 * lane + 256 * j), c4 = *(const f32x4*)(sc + 4 * lane + 256 * j);
;                 const f32x4 u = v[j] * (c4 + 1.f) + s4; u32x2 o; o.x = pk_bf16(u[0], u[1]); o.y = pk_bf16(u[2], u[3]);
;                 *(u32x2*)(U + (size_t)row * D + 4 * lane + 256 * j) = o; }
	v_fmac_f32_e32 v45, v54, v54
	v_fmac_f32_e32 v68, v56, v56
	v_fmac_f32_e32 v69, v58, v58
	v_mul_f32_e32 v72, v65, v65
	v_mul_f32_e32 v73, v67, v67
	v_fmac_f32_e32 v70, v60, v60
	v_fmac_f32_e32 v71, v62, v62
	v_add_f32_e32 v33, v33, v45
	v_add_f32_e32 v45, v68, v69
	v_fmac_f32_e32 v72, v64, v64
	v_fmac_f32_e32 v73, v66, v66
	v_add_f32_e32 v68, v70, v71
	v_add_f32_e32 v33, v33, v45
	v_add_f32_e32 v69, v72, v73
	v_add_f32_e32 v33, v68, v33
	v_add_f32_e32 v33, v69, v33
	s_nop 1
	v_add_f32_dpp v33, v33, v33 quad_perm:[1,0,3,2] row_mask:0xf bank_mask:0xf bound_ctrl:1
	s_nop 1
	v_add_f32_dpp v33, v33, v33 quad_perm:[2,3,0,1] row_mask:0xf bank_mask:0xf bound_ctrl:1
	s_nop 1
	v_add_f32_dpp v33, v33, v33 row_half_mirror row_mask:0xf bank_mask:0xf bound_ctrl:1
	s_nop 1
	v_add_f32_dpp v33, v33, v33 row_mirror row_mask:0xf bank_mask:0xf bound_ctrl:1
	v_mov_b32_e32 v45, v33
	s_nop 1
	v_permlane16_swap_b32_e32 v33, v45
	v_add_f32_e32 v33, v33, v45
	v_mov_b32_e32 v45, v33
	s_nop 1
	v_permlane32_swap_b32_e32 v33, v45
	v_add_f32_e32 v33, v33, v45
	v_fmamk_f32 v33, v33, 0x3a800000, v198
	v_mul_f32_e32 v45, 0x4b800000, v33
	v_cmp_gt_f32_e32 vcc, s25, v33
	s_nop 1
	v_cndmask_b32_e32 v33, v33, v45, vcc
	v_rsq_f32_e32 v33, v33
	s_nop 0
	v_mul_f32_e32 v45, 0x45800000, v33
	v_cndmask_b32_e32 v68, v33, v45, vcc
	v_pk_mul_f32 v[54:55], v[54:55], v[68:69] op_sel_hi:[1,0]
	v_pk_mul_f32 v[52:53], v[52:53], v[68:69] op_sel_hi:[1,0]
	v_pk_mul_f32 v[56:57], v[56:57], v[68:69] op_sel_hi:[1,0]
	v_pk_mul_f32 v[58:59], v[58:59], v[68:69] op_sel_hi:[1,0]
	v_pk_mul_f32 v[60:61], v[60:61], v[68:69] op_sel_hi:[1,0]
	v_pk_mul_f32 v[62:63], v[62:63], v[68:69] op_sel_hi:[1,0]
	v_pk_mul_f32 v[64:65], v[64:65], v[68:69] op_sel_hi:[1,0]
	v_pk_mul_f32 v[66:67], v[66:67], v[68:69] op_sel_hi:[1,0]
	v_pk_fma_f32 v[8:9], v[112:113], v[52:53], v[128:129]
	v_pk_fma_f32 v[10:11], v[114:115], v[54:55], v[130:131]
	v_pk_fma_f32 v[18:19], v[106:107], v[58:59], v[122:123]
	v_pk_fma_f32 v[16:17], v[104:105], v[56:57], v[120:121]
	v_pk_fma_f32 v[14:15], v[118:119], v[62:63], v[134:135]
	v_pk_fma_f32 v[12:13], v[116:117], v[60:61], v[132:133]
	v_pk_fma_f32 v[22:23], v[110:111], v[66:67], v[126:127]
	v_pk_fma_f32 v[20:21], v[108:109], v[64:65], v[124:125]
	v_cvt_pk_f16_f32 v1, v10, v11
	v_cvt_pk_f16_f32 v0, v8, v9
	v_cvt_pk_f16_f32 v3, v18, v19
	v_cvt_pk_f16_f32 v2, v16, v17
	v_cvt_pk_f16_f32 v5, v14, v15
	v_cvt_pk_f16_f32 v4, v12, v13
	v_cvt_pk_f16_f32 v7, v22, v23
	v_cvt_pk_f16_f32 v6, v20, v21
	global_store_dwordx2 v[50:51], v[0:1], off nt
	global_store_dwordx2 v[50:51], v[2:3], off offset:512 nt
	global_store_dwordx2 v[50:51], v[4:5], off offset:1024 nt
	global_store_dwordx2 v[50:51], v[6:7], off offset:1536 nt
	v_lshl_add_u64 v[24:25], v[48:49], 0, s[44:45]
	v_cmp_lt_i32_e32 vcc, s20, v32
	s_or_b64 s[40:41], vcc, s[40:41]
	v_pk_add_f32 v[0:1], v[208:209], 1.0 op_sel_hi:[1,0]
	v_pk_add_f32 v[2:3], v[210:211], 1.0 op_sel_hi:[1,0]
	v_pk_fma_f32 v[0:1], v[8:9], v[0:1], v[212:213]
	v_pk_fma_f32 v[2:3], v[10:11], v[2:3], v[214:215]
	v_cvt_pk_bf16_f32 v0, v0, v1
	s_nop 0
	v_cvt_pk_bf16_f32 v1, v2, v3
	flat_store_dwordx2 v[46:47], v[0:1]
	v_pk_add_f32 v[0:1], v[216:217], 1.0 op_sel_hi:[1,0]
	v_pk_add_f32 v[2:3], v[218:219], 1.0 op_sel_hi:[1,0]
	v_pk_fma_f32 v[0:1], v[16:17], v[0:1], v[220:221]
	v_pk_fma_f32 v[2:3], v[18:19], v[2:3], v[222:223]
	v_cvt_pk_bf16_f32 v0, v0, v1
	s_nop 0
	v_cvt_pk_bf16_f32 v1, v2, v3
	flat_store_dwordx2 v[46:47], v[0:1] offset:512
	v_pk_add_f32 v[0:1], v[224:225], 1.0 op_sel_hi:[1,0]
	v_pk_add_f32 v[2:3], v[226:227], 1.0 op_sel_hi:[1,0]
	v_pk_fma_f32 v[0:1], v[12:13], v[0:1], v[228:229]
	v_pk_fma_f32 v[2:3], v[14:15], v[2:3], v[230:231]
	v_cvt_pk_bf16_f32 v0, v0, v1
	s_nop 0
	v_cvt_pk_bf16_f32 v1, v2, v3
	flat_store_dwordx2 v[46:47], v[0:1] offset:1024
	v_pk_add_f32 v[0:1], v[232:233], 1.0 op_sel_hi:[1,0]
	v_pk_add_f32 v[2:3], v[234:235], 1.0 op_sel_hi:[1,0]
	v_pk_fma_f32 v[0:1], v[20:21], v[0:1], v[236:237]
	v_pk_fma_f32 v[2:3], v[22:23], v[2:3], v[238:239]
	v_cvt_pk_bf16_f32 v0, v0, v1
	s_nop 0
	v_cvt_pk_bf16_f32 v1, v2, v3
	flat_store_dwordx2 v[46:47], v[0:1] offset:1536
	s_andn2_b64 exec, exec, s[40:41]
	s_cbranch_execnz .LBB0_114

; DI int obid() { int b = blockIdx.x; asm volatile("" : "+s"(b)); return b; }
; DI f32x4 h4_to_f4(u32x2 t) { const h16x4 h = __builtin_bit_cast(h16x4, t); return (f32x4){(float)h[0], (float)h[1], (float)h[2], (float)h[3]}; }
; DI void phase_row(const Params& P, const void* xs, int sh, void* xd, int dh, int ln, int gl, int gidx, float wgt, int modl, int shidx, bool dry = false) {
;     ...
;     for (int row = obid() * 8 + w; row < T; row += gridDim.x * 8) {
;         const int b = row >= SEQ;
;         f32x4 v[4];
; #pragma unroll
;         for (int j = 0; j < 4; ++j) { const size_t e = (size_t)row * D + 4 * lane + 256 * j;
;             if (sh) v[j] = h4_to_f4(__builtin_nontemporal_load((const u32x2*)((const unsigned short*)xs + e))); else v[j] = __builtin_nontemporal_load((const f32x4*)((const float*)xs + e)); }
;         if (ln >= 0) {
;             u32x2 fv[4];
; #pragma unroll
;             for (int j = 0; j < 4; ++j) fv[j] = __builtin_nontemporal_load((const u32x2*)(U + (size_t)row * D + 4 * lane + 256 * j));
;             const float* gate = mod + (gl * 2 + b) * 9216 + gidx * 1024;
; #pragma unroll
;             for (int j = 0; j < 4; ++j) { const f32x4 g = (*(const f32x4*)(gate + 4 * lane + 256 * j) + 1.f) * wgt;
;     ...
;             const float* shp = mod + (modl * 2 + b) * 9216 + shidx * 1024; const float* sc = shp + 1024;
; #pragma unroll
;             for (int j = 0; j < 4; ++j) { const f32x4 s4 = *(const f32x4*)(shp + 4 * lane + 256 * j), c4 = *(const f32x4*)(sc + 4 * lane + 256 * j);
.LBB0_227:
	s_mov_b64 s[60:61], 0
	s_and_b64 vcc, exec, s[2:3]
	s_cbranch_vccz .LBB0_239
	v_readlane_b32 s8, v245, 33
	s_cmp_gt_i32 s8, 0
	s_cbranch_scc0 .LBB0_248
	s_cmp_gt_i32 s8, 3
	s_mov_b64 s[2:3], -1
	s_cbranch_scc0 .LBB0_236
	v_readlane_b32 s2, v245, 33
	s_cmp_eq_u32 s2, 4
	s_mov_b64 s[48:49], -1
	s_cbranch_scc0 .LBB0_235
	s_waitcnt vmcnt(0)
	v_mov_b32_e32 v0, v195
	s_load_dwordx8 s[52:59], s[84:85], 0xc8
	v_ashrrev_i32_e32 v1, 6, v0
	s_mov_b32 s2, s28
	s_waitcnt lgkmcnt(0)
	s_mov_b64 s[8:9], s[58:59]
	s_mov_b64 s[10:11], s[58:59]
	s_nop 0
	v_lshl_add_u32 v32, s2, 3, v1
	v_cmp_gt_i32_e32 vcc, s75, v32
	s_and_saveexec_b64 s[2:3], vcc
	s_load_dwordx16 s[40:55], s[84:85], 0x0
	s_mov_b32 s18, 0x3fb504f3
	s_mov_b64 s[26:27], 0x1000
	s_cbranch_execz .LBB0_234
	v_lshlrev_b32_e32 v0, 2, v0
	v_and_b32_e32 v34, 0xfc, v0
	v_lshlrev_b32_e32 v184, 1, v34
	v_lshl_add_u64 v[0:1], s[10:11], 0, v[184:185]
	s_mov_b64 s[10:11], 0x5808000
	v_lshlrev_b32_e32 v184, 2, v34
	v_lshl_add_u64 v[36:37], v[0:1], 0, s[10:11]
	v_lshl_add_u64 v[0:1], s[8:9], 0, v[184:185]
	s_mov_b64 s[10:11], 0x5582000
	s_add_u32 s8, s8, 0x5583000
	v_lshl_add_u64 v[38:39], v[0:1], 0, s[10:11]
	s_addc_u32 s9, s9, 0
	s_waitcnt lgkmcnt(0)
	v_lshl_add_u64 v[40:41], s[54:55], 0, v[184:185]
	v_lshl_add_u64 v[42:43], s[4:5], 0, v[184:185]
	s_mov_b64 s[4:5], 0
	global_load_dwordx4 v[108:111], v[40:41], off
	global_load_dwordx4 v[100:103], v[40:41], off offset:1024
	global_load_dwordx4 v[124:127], v[42:43], off
	global_load_dwordx4 v[116:119], v[42:43], off offset:1024
	global_load_dwordx4 v[112:115], v[40:41], off offset:2048
	global_load_dwordx4 v[104:107], v[40:41], off offset:3072
	global_load_dwordx4 v[128:131], v[42:43], off offset:2048
	global_load_dwordx4 v[120:123], v[42:43], off offset:3072
	v_mov_b32_e32 v184, 0
	v_lshl_add_u64 v[164:165], v[38:39], 0, v[184:185]
	flat_load_dwordx4 v[132:135], v[164:165]
	flat_load_dwordx4 v[136:139], v[164:165] offset:1024
	flat_load_dwordx4 v[140:143], v[164:165] offset:2048
	flat_load_dwordx4 v[144:147], v[164:165] offset:3072
	v_mov_b32_e32 v184, v203
	v_lshl_add_u64 v[164:165], v[38:39], 0, v[184:185]
	flat_load_dwordx4 v[148:151], v[164:165]
	flat_load_dwordx4 v[152:155], v[164:165] offset:1024
	flat_load_dwordx4 v[156:159], v[164:165] offset:2048
	flat_load_dwordx4 v[160:163], v[164:165] offset:3072
	s_waitcnt vmcnt(0) lgkmcnt(0)
	s_mov_b64 s[100:101], 1
.LBB0_233:
	v_cmp_lt_i32_e32 vcc, s23, v32
	v_ashrrev_i32_e32 v33, 31, v32
	v_lshlrev_b64 v[46:47], 11, v[32:33]
	v_cndmask_b32_e32 v184, 0, v203, vcc
	v_lshl_add_u64 v[44:45], v[38:39], 0, v[184:185]
	v_lshlrev_b64 v[48:49], 10, v[32:33]
	v_cndmask_b32_e32 v50, v132, v148, vcc
	v_cndmask_b32_e32 v51, v133, v149, vcc
	v_cndmask_b32_e32 v52, v134, v150, vcc
	v_cndmask_b32_e32 v53, v135, v151, vcc
	v_cndmask_b32_e32 v54, v136, v152, vcc
	v_cndmask_b32_e32 v55, v137, v153, vcc
	v_cndmask_b32_e32 v56, v138, v154, vcc
	v_cndmask_b32_e32 v57, v139, v155, vcc
	v_cndmask_b32_e32 v58, v140, v156, vcc
	v_cndmask_b32_e32 v59, v141, v157, vcc
	v_cndmask_b32_e32 v60, v142, v158, vcc
	v_cndmask_b32_e32 v61, v143, v159, vcc
	v_cndmask_b32_e32 v62, v144, v160, vcc
	v_cndmask_b32_e32 v63, v145, v161, vcc
	v_cndmask_b32_e32 v64, v146, v162, vcc
	v_cndmask_b32_e32 v65, v147, v163, vcc
	v_lshl_add_u64 v[44:45], v[36:37], 0, v[46:47]
	v_or_b32_e32 v48, v48, v34
	flat_load_dwordx2 v[82:83], v[44:45] nt
	flat_load_dwordx2 v[84:85], v[44:45] offset:512 nt
	flat_load_dwordx2 v[86:87], v[44:45] offset:1024 nt
	flat_load_dwordx2 v[88:89], v[44:45] offset:1536 nt
	v_lshl_add_u64 v[66:67], s[8:9], 0, v[184:185]
	v_lshlrev_b32_e32 v184, 2, v34
	v_lshl_add_u64 v[78:79], v[48:49], 2, s[40:41]
	v_lshl_add_u64 v[46:47], v[66:67], 0, v[184:185]
	s_cmp_eq_u64 vcc, s[100:101]
	s_cbranch_scc1 .Lrow_keep_4
	s_mov_b64 s[100:101], vcc
	v_lshl_add_u64 v[164:165], v[46:47], 0, s[26:27]
	flat_load_dwordx4 v[208:211], v[164:165]
	flat_load_dwordx4 v[212:215], v[46:47]
	flat_load_dwordx4 v[216:219], v[164:165] offset:1024
	flat_load_dwordx4 v[220:223], v[46:47] offset:1024
	flat_load_dwordx4 v[224:227], v[164:165] offset:2048
	flat_load_dwordx4 v[228:231], v[46:47] offset:2048
	flat_load_dwordx4 v[232:235], v[164:165] offset:3072
	flat_load_dwordx4 v[236:239], v[46:47] offset:3072
; DI float bf_lo(unsigned u) { return __uint_as_float(u << 16); }
; DI float bf_hi(unsigned u) { return __uint_as_float(u & 0xffff0000u); }
; DI f32x4 h4_to_f4(u32x2 t) { const h16x4 h = __builtin_bit_cast(h16x4, t); return (f32x4){(float)h[0], (float)h[1], (float)h[2], (float)h[3]}; }
; DI void phase_row(const Params& P, const void* xs, int sh, void* xd, int dh, int ln, int gl, int gidx, float wgt, int modl, int shidx, bool dry = false) {
;     ...
;             if (sh) v[j] = h4_to_f4(__builtin_nontemporal_load((const u32x2*)((const unsigned short*)xs + e))); else v[j] = __builtin_nontemporal_load((const f32x4*)((const float*)xs + e)); }
;         if (ln >= 0) {
;             u32x2 fv[4];
; #pragma unroll
;             for (int j = 0; j < 4; ++j) fv[j] = __builtin_nontemporal_load((const u32x2*)(U + (size_t)row * D + 4 * lane + 256 * j));
;             const float* gate = mod + (gl * 2 + b) * 9216 + gidx * 1024;
; #pragma unroll
;             for (int j = 0; j < 4; ++j) { const f32x4 g = (*(const f32x4*)(gate + 4 * lane + 256 * j) + 1.f) * wgt;
;                 const f32x4 f = {bf_lo(fv[j].x), bf_hi(fv[j].x), bf_lo(fv[j].y), bf_hi(fv[j].y)};
;                 v[j] = v[j] * DN_ALPHA + g * f; }
;             float s = 0.f;
; #pragma unroll
;             for (int j = 0; j < 4; ++j) s += (v[j][0] + v[j][1]) + (v[j][2] + v[j][3]);
;             const float mean = wave_sum(s, lane) * (1.f / 1024.f);
;             float q = 0.f;
; #pragma unroll
;             for (int j = 0; j < 4; ++j) { v[j] = v[j] - mean; q += (v[j][0] * v[j][0] + v[j][1] * v[j][1]) + (v[j][2] * v[j][2] + v[j][3] * v[j][3]); }
.Lrow_keep_4:
	global_load_dwordx4 v[66:69], v[78:79], off nt
	global_load_dwordx4 v[70:73], v[78:79], off offset:1024 nt
	global_load_dwordx4 v[74:77], v[78:79], off offset:2048 nt
	s_nop 0
	global_load_dwordx4 v[78:81], v[78:79], off offset:3072 nt
	v_add_co_u32_e32 v90, vcc, s1, v46
	v_lshl_add_u64 v[48:49], v[48:49], 1, s[56:57]
	s_nop 0
	v_addc_co_u32_e32 v91, vcc, 0, v47, vcc
	v_add_u32_e32 v32, s70, v32
	s_waitcnt vmcnt(0) lgkmcnt(0)
	v_pk_add_f32 v[52:53], v[52:53], 1.0 op_sel_hi:[1,0]
	v_pk_add_f32 v[50:51], v[50:51], 1.0 op_sel_hi:[1,0]
	v_pk_add_f32 v[56:57], v[56:57], 1.0 op_sel_hi:[1,0]
	v_pk_add_f32 v[54:55], v[54:55], 1.0 op_sel_hi:[1,0]
	v_lshlrev_b32_e32 v92, 16, v82
	v_and_b32_e32 v93, 0xffff0000, v82
	v_lshlrev_b32_e32 v82, 16, v83
	v_and_b32_e32 v83, 0xffff0000, v83
	v_pk_mul_f32 v[52:53], v[52:53], 0.5 op_sel_hi:[1,0]
	v_pk_mul_f32 v[50:51], v[50:51], 0.5 op_sel_hi:[1,0]
	v_pk_add_f32 v[60:61], v[60:61], 1.0 op_sel_hi:[1,0]
	v_pk_add_f32 v[58:59], v[58:59], 1.0 op_sel_hi:[1,0]
	v_lshlrev_b32_e32 v94, 16, v84
	v_and_b32_e32 v95, 0xffff0000, v84
	v_lshlrev_b32_e32 v84, 16, v85
	v_and_b32_e32 v85, 0xffff0000, v85
	v_pk_mul_f32 v[56:57], v[56:57], 0.5 op_sel_hi:[1,0]
	v_pk_mul_f32 v[54:55], v[54:55], 0.5 op_sel_hi:[1,0]
	v_pk_mul_f32 v[52:53], v[52:53], v[82:83]
	v_pk_mul_f32 v[50:51], v[50:51], v[92:93]
	v_pk_add_f32 v[64:65], v[64:65], 1.0 op_sel_hi:[1,0]
	v_pk_add_f32 v[62:63], v[62:63], 1.0 op_sel_hi:[1,0]
	v_lshlrev_b32_e32 v96, 16, v86
	v_and_b32_e32 v97, 0xffff0000, v86
	v_lshlrev_b32_e32 v86, 16, v87
	v_and_b32_e32 v87, 0xffff0000, v87
	v_pk_mul_f32 v[60:61], v[60:61], 0.5 op_sel_hi:[1,0]
	v_pk_mul_f32 v[58:59], v[58:59], 0.5 op_sel_hi:[1,0]
	v_pk_mul_f32 v[56:57], v[56:57], v[84:85]
	v_pk_mul_f32 v[54:55], v[54:55], v[94:95]
	v_pk_fma_f32 v[52:53], v[68:69], s[18:19], v[52:53] op_sel_hi:[1,0,1]
	v_pk_fma_f32 v[50:51], v[66:67], s[18:19], v[50:51] op_sel_hi:[1,0,1]
	v_lshlrev_b32_e32 v98, 16, v88
	v_and_b32_e32 v99, 0xffff0000, v88
	v_lshlrev_b32_e32 v88, 16, v89
	v_and_b32_e32 v89, 0xffff0000, v89
	v_pk_mul_f32 v[64:65], v[64:65], 0.5 op_sel_hi:[1,0]
	v_pk_mul_f32 v[62:63], v[62:63], 0.5 op_sel_hi:[1,0]
	v_pk_mul_f32 v[60:61], v[60:61], v[86:87]
	v_pk_mul_f32 v[58:59], v[58:59], v[96:97]
	v_pk_fma_f32 v[56:57], v[72:73], s[18:19], v[56:57] op_sel_hi:[1,0,1]
	v_pk_fma_f32 v[54:55], v[70:71], s[18:19], v[54:55] op_sel_hi:[1,0,1]
	v_add_f32_e32 v33, v50, v51
	v_add_f32_e32 v35, v52, v53
	v_pk_mul_f32 v[64:65], v[64:65], v[88:89]
	v_pk_mul_f32 v[62:63], v[62:63], v[98:99]
	v_pk_fma_f32 v[60:61], v[76:77], s[18:19], v[60:61] op_sel_hi:[1,0,1]
	v_pk_fma_f32 v[58:59], v[74:75], s[18:19], v[58:59] op_sel_hi:[1,0,1]
	v_add_f32_e32 v66, v54, v55
	v_add_f32_e32 v67, v56, v57
	v_add_f32_e32 v33, v33, v35
	v_pk_fma_f32 v[64:65], v[80:81], s[18:19], v[64:65] op_sel_hi:[1,0,1]
	v_pk_fma_f32 v[62:63], v[78:79], s[18:19], v[62:63] op_sel_hi:[1,0,1]
	v_add_f32_e32 v68, v58, v59
	v_add_f32_e32 v69, v60, v61
	v_add_f32_e32 v35, v66, v67
	v_add_f32_e32 v33, 0, v33
	v_add_f32_e32 v70, v62, v63
	v_add_f32_e32 v71, v64, v65
	v_add_f32_e32 v66, v68, v69
	v_add_f32_e32 v33, v33, v35
	v_add_f32_e32 v67, v70, v71
	v_add_f32_e32 v33, v33, v66
	v_add_f32_e32 v33, v33, v67
	s_nop 1
	v_add_f32_dpp v33, v33, v33 quad_perm:[1,0,3,2] row_mask:0xf bank_mask:0xf bound_ctrl:1
	s_nop 1
	v_add_f32_dpp v33, v33, v33 quad_perm:[2,3,0,1] row_mask:0xf bank_mask:0xf bound_ctrl:1
	s_nop 1
	v_add_f32_dpp v33, v33, v33 row_half_mirror row_mask:0xf bank_mask:0xf bound_ctrl:1
	s_nop 1
	v_add_f32_dpp v33, v33, v33 row_mirror row_mask:0xf bank_mask:0xf bound_ctrl:1
	v_mov_b32_e32 v35, v33
	s_nop 1
	v_permlane16_swap_b32_e32 v33, v35
	v_add_f32_e32 v33, v33, v35
	v_mov_b32_e32 v35, v33
	s_nop 1
	v_permlane32_swap_b32_e32 v33, v35
	v_add_f32_e32 v33, v33, v35
	v_fmac_f32_e32 v53, 0xba800000, v33
	v_fmac_f32_e32 v51, 0xba800000, v33
	v_fmac_f32_e32 v57, 0xba800000, v33
	v_fmac_f32_e32 v55, 0xba800000, v33
	v_fmamk_f32 v52, v33, 0xba800000, v52
	v_fmamk_f32 v50, v33, 0xba800000, v50
	v_fmamk_f32 v56, v33, 0xba800000, v56
	v_fmamk_f32 v54, v33, 0xba800000, v54
	v_fmamk_f32 v60, v33, 0xba800000, v60
	v_fmac_f32_e32 v61, 0xba800000, v33
	v_fmamk_f32 v58, v33, 0xba800000, v58
	v_fmac_f32_e32 v59, 0xba800000, v33
	v_fmamk_f32 v64, v33, 0xba800000, v64
	v_fmac_f32_e32 v65, 0xba800000, v33
	v_fmamk_f32 v62, v33, 0xba800000, v62
	v_fmac_f32_e32 v63, 0xba800000, v33
; DI unsigned pk_bf16(float lo, float hi) { unsigned r; asm("v_cvt_pk_bf16_f32 %0, %1, %2" : "=v"(r) : "v"(lo), "v"(hi)); return r; }
; DI void phase_row(const Params& P, const void* xs, int sh, void* xd, int dh, int ln, int gl, int gidx, float wgt, int modl, int shidx, bool dry = false) {
;     ...
;             for (int j = 0; j < 4; ++j) { v[j] = v[j] - mean; q += (v[j][0] * v[j][0] + v[j][1] * v[j][1]) + (v[j][2] * v[j][2] + v[j][3] * v[j][3]); }
;             const float rstd = rsqrtf(wave_sum(q, lane) * (1.f / 1024.f) + LN_EPS);
; #pragma unroll
;             for (int j = 0; j < 4; ++j) { const f32x4 g = *(const f32x4*)(P.ln_g + ln * D + 4 * lane + 256 * j), bb = *(const f32x4*)(P.ln_b + ln * D + 4 * lane + 256 * j); v[j] = v[j] * rstd * g + bb; }
;             if (dry) { if (v[0][0] + v[1][1] + v[2][2] + v[3][3] == 12345.678f) P.xbuf[row] = 0.f; continue; }
; #pragma unroll
;             for (int j = 0; j < 4; ++j) { const size_t e = (size_t)row * D + 4 * lane + 256 * j;
;                 if (dh) __builtin_nontemporal_store(f4_to_h4(v[j]), (u32x2*)((unsigned short*)xd + e)); else __builtin_nontemporal_store(v[j], (f32x4*)((float*)xd + e)); }
;         }
;         if (modl >= 0) {
;             const float* shp = mod + (modl * 2 + b) * 9216 + shidx * 1024; const float* sc = shp + 1024;
; #pragma unroll
;             for (int j = 0; j < 4; ++j) { const f32x4 s4 = *(const f32x4*)(shp + 4 * lane + 256 * j), c4 = *(const f32x4*)(sc + 4 * lane + 256 * j);
;                 const f32x4 u = v[j] * (c4 + 1.f) + s4; u32x2 o; o.x = pk_bf16(u[0], u[1]); o.y = pk_bf16(u[2], u[3]);
;                 *(u32x2*)(U + (size_t)row * D + 4 * lane + 256 * j) = o; }
	v_mul_f32_e32 v33, v51, v51
	v_mul_f32_e32 v35, v53, v53
	v_mul_f32_e32 v66, v55, v55
	v_mul_f32_e32 v67, v57, v57
	v_mul_f32_e32 v68, v59, v59
	v_mul_f32_e32 v69, v61, v61
	v_fmac_f32_e32 v33, v50, v50
	v_fmac_f32_e32 v35, v52, v52
	v_fmac_f32_e32 v66, v54, v54
	v_fmac_f32_e32 v67, v56, v56
	v_mul_f32_e32 v70, v63, v63
	v_mul_f32_e32 v71, v65, v65
	v_fmac_f32_e32 v68, v58, v58
	v_fmac_f32_e32 v69, v60, v60
	v_add_f32_e32 v33, v33, v35
	v_add_f32_e32 v35, v66, v67
	v_fmac_f32_e32 v70, v62, v62
	v_fmac_f32_e32 v71, v64, v64
	v_add_f32_e32 v66, v68, v69
	v_add_f32_e32 v33, v33, v35
	v_add_f32_e32 v67, v70, v71
	v_add_f32_e32 v33, v66, v33
	v_add_f32_e32 v33, v67, v33
	s_nop 1
	v_add_f32_dpp v33, v33, v33 quad_perm:[1,0,3,2] row_mask:0xf bank_mask:0xf bound_ctrl:1
	s_nop 1
	v_add_f32_dpp v33, v33, v33 quad_perm:[2,3,0,1] row_mask:0xf bank_mask:0xf bound_ctrl:1
	s_nop 1
	v_add_f32_dpp v33, v33, v33 row_half_mirror row_mask:0xf bank_mask:0xf bound_ctrl:1
	s_nop 1
	v_add_f32_dpp v33, v33, v33 row_mirror row_mask:0xf bank_mask:0xf bound_ctrl:1
	v_mov_b32_e32 v35, v33
	s_nop 1
	v_permlane16_swap_b32_e32 v33, v35
	v_add_f32_e32 v33, v33, v35
	v_mov_b32_e32 v35, v33
	s_nop 1
	v_permlane32_swap_b32_e32 v33, v35
	v_add_f32_e32 v33, v33, v35
	v_fmamk_f32 v33, v33, 0x3a800000, v198
	v_mul_f32_e32 v35, 0x4b800000, v33
	v_cmp_gt_f32_e32 vcc, s25, v33
	s_nop 1
	v_cndmask_b32_e32 v33, v33, v35, vcc
	v_rsq_f32_e32 v33, v33
	s_nop 0
	v_mul_f32_e32 v35, 0x45800000, v33
	v_cndmask_b32_e32 v66, v33, v35, vcc
	v_pk_mul_f32 v[52:53], v[52:53], v[66:67] op_sel_hi:[1,0]
	v_pk_mul_f32 v[50:51], v[50:51], v[66:67] op_sel_hi:[1,0]
	v_pk_mul_f32 v[54:55], v[54:55], v[66:67] op_sel_hi:[1,0]
	v_pk_mul_f32 v[56:57], v[56:57], v[66:67] op_sel_hi:[1,0]
	v_pk_mul_f32 v[58:59], v[58:59], v[66:67] op_sel_hi:[1,0]
	v_pk_mul_f32 v[60:61], v[60:61], v[66:67] op_sel_hi:[1,0]
	v_pk_mul_f32 v[62:63], v[62:63], v[66:67] op_sel_hi:[1,0]
	v_pk_mul_f32 v[64:65], v[64:65], v[66:67] op_sel_hi:[1,0]
	v_pk_fma_f32 v[8:9], v[108:109], v[50:51], v[124:125]
	v_pk_fma_f32 v[10:11], v[110:111], v[52:53], v[126:127]
	v_pk_fma_f32 v[18:19], v[102:103], v[56:57], v[118:119]
	v_pk_fma_f32 v[16:17], v[100:101], v[54:55], v[116:117]
	v_pk_fma_f32 v[14:15], v[114:115], v[60:61], v[130:131]
	v_pk_fma_f32 v[12:13], v[112:113], v[58:59], v[128:129]
	v_pk_fma_f32 v[22:23], v[106:107], v[64:65], v[122:123]
	v_pk_fma_f32 v[20:21], v[104:105], v[62:63], v[120:121]
	v_cvt_pk_f16_f32 v1, v10, v11
	v_cvt_pk_f16_f32 v0, v8, v9
	v_cvt_pk_f16_f32 v3, v18, v19
	v_cvt_pk_f16_f32 v2, v16, v17
	v_cvt_pk_f16_f32 v5, v14, v15
	v_cvt_pk_f16_f32 v4, v12, v13
	v_cvt_pk_f16_f32 v7, v22, v23
	v_cvt_pk_f16_f32 v6, v20, v21
	global_store_dwordx2 v[48:49], v[0:1], off nt
	global_store_dwordx2 v[48:49], v[2:3], off offset:512 nt
	global_store_dwordx2 v[48:49], v[4:5], off offset:1024 nt
	global_store_dwordx2 v[48:49], v[6:7], off offset:1536 nt
	v_lshl_add_u64 v[24:25], v[46:47], 0, s[26:27]
	v_cmp_lt_i32_e32 vcc, s20, v32
	s_or_b64 s[4:5], vcc, s[4:5]
	v_pk_add_f32 v[0:1], v[208:209], 1.0 op_sel_hi:[1,0]
	v_pk_add_f32 v[2:3], v[210:211], 1.0 op_sel_hi:[1,0]
	v_pk_fma_f32 v[0:1], v[8:9], v[0:1], v[212:213]
	v_pk_fma_f32 v[2:3], v[10:11], v[2:3], v[214:215]
	v_cvt_pk_bf16_f32 v0, v0, v1
	s_nop 0
	v_cvt_pk_bf16_f32 v1, v2, v3
	flat_store_dwordx2 v[44:45], v[0:1]
	v_pk_add_f32 v[0:1], v[216:217], 1.0 op_sel_hi:[1,0]
	v_pk_add_f32 v[2:3], v[218:219], 1.0 op_sel_hi:[1,0]
	v_pk_fma_f32 v[0:1], v[16:17], v[0:1], v[220:221]
	v_pk_fma_f32 v[2:3], v[18:19], v[2:3], v[222:223]
	v_cvt_pk_bf16_f32 v0, v0, v1
	s_nop 0
	v_cvt_pk_bf16_f32 v1, v2, v3
	flat_store_dwordx2 v[44:45], v[0:1] offset:512
	v_pk_add_f32 v[0:1], v[224:225], 1.0 op_sel_hi:[1,0]
	v_pk_add_f32 v[2:3], v[226:227], 1.0 op_sel_hi:[1,0]
	v_pk_fma_f32 v[0:1], v[12:13], v[0:1], v[228:229]
	v_pk_fma_f32 v[2:3], v[14:15], v[2:3], v[230:231]
	v_cvt_pk_bf16_f32 v0, v0, v1
	s_nop 0
	v_cvt_pk_bf16_f32 v1, v2, v3
	flat_store_dwordx2 v[44:45], v[0:1] offset:1024
	v_pk_add_f32 v[0:1], v[232:233], 1.0 op_sel_hi:[1,0]
	v_pk_add_f32 v[2:3], v[234:235], 1.0 op_sel_hi:[1,0]
	v_pk_fma_f32 v[0:1], v[20:21], v[0:1], v[236:237]
	v_pk_fma_f32 v[2:3], v[22:23], v[2:3], v[238:239]
	v_cvt_pk_bf16_f32 v0, v0, v1
	s_nop 0
	v_cvt_pk_bf16_f32 v1, v2, v3
	flat_store_dwordx2 v[44:45], v[0:1] offset:1536
	s_andn2_b64 exec, exec, s[4:5]
	s_cbranch_execnz .LBB0_233
